# write-through (sc0 sc1) GEMM epilogue stores in P1 and P5: nothing left for the L2 write-back at the grid barrier
# speedup vs baseline: 1.0010x; 1.0010x over previous
; #define PG8_STAGE(bufoff, gbase, voff) do { _Pragma("unroll") for (int _i = 0; _i < 2; ++_i) \
;         __builtin_amdgcn_global_load_lds((const unsigned*)((const char*)(gbase) + (voff)[_i]), (LAS unsigned*)(lds + (bufoff) + ldsw + _i * 8192), 16, 0, 0); } while (0)
; #define PG8_LDA(dst, b, h) do { _Pragma("unroll") for (int m = 0; m < 4; ++m) _Pragma("unroll") for (int k = 0; k < 2; ++k) dst[m][k] = *(const LAS h16x8*)(lds + PG8_SA(b, h) + aoff + m * 2048 + k * 1024); } while (0)
; #define PG8_LDB(dst, b, h) do { _Pragma("unroll") for (int n = 0; n < 2; ++n) _Pragma("unroll") for (int k = 0; k < 2; ++k) dst[n][k] = *(const LAS h16x8*)(lds + PG8_SB(b, h) + boff + n * 2048 + k * 1024); } while (0)
; #define PG8_MMA(ai, bj, At, Bt) do { __builtin_amdgcn_s_setprio(1); _Pragma("unroll") for (int m = 0; m < 4; ++m) _Pragma("unroll") for (int n = 0; n < 2; ++n) _Pragma("unroll") for (int k = 0; k < 2; ++k) \
;         acc[ai][bj][m][n] = __builtin_amdgcn_mfma_f32_16x16x32_f16(Bt[n][k], At[m][k], acc[ai][bj][m][n], 0, 0, 0); __builtin_amdgcn_s_setprio(0); } while (0)
; #define PG8_WAIT_L(n) asm volatile("s_waitcnt lgkmcnt(" #n ")" ::: "memory")
; #define PG8_BAR __builtin_amdgcn_s_barrier()
; #define PG8_SCHED __builtin_amdgcn_sched_barrier(0)
; template <class Epi>
; __device__ __forceinline__ void gemm_phase(LAS unsigned char* lds, const Gemm g, const StaticOrder& S, const Epi& E) {
;     ...
;             PG8_LDB(B0, 0, 0); PG8_SCHED; PG8_LDA(At, 0, 0); PG8_STAGE(PG8_SA(1, 1), a1 + hstep, voffA);
;             PG8_WAIT_L(8); PG8_BAR; PG8_WAIT_L(0); PG8_MMA(0, 0, At, B0); PG8_BAR; PG8_SCHED;
;             PG8_LDB(B1, 0, 1); PG8_STAGE(PG8_SB(0, 0), b2, voffB);
;             PG8_BAR; PG8_WAIT_L(0); PG8_MMA(0, 1, At, B1); PG8_BAR;
;             PG8_LDA(At, 0, 1); PG8_STAGE(PG8_SA(0, 0), a2, voffA);
;             PG8_BAR; PG8_WAIT_L(0); PG8_MMA(1, 0, At, B0); PG8_BAR; PG8_SCHED;
.LBB0_84:
	ds_read_b128 v[162:165], v158
	ds_read_b128 v[166:169], v158 offset:1024
	ds_read_b128 v[170:173], v158 offset:2048
	ds_read_b128 v[174:177], v158 offset:3072
	s_add_u32 s38, s34, 0xfffc0080
	s_addc_u32 s39, s35, -1
	s_cmp_eq_u32 s96, 12
	s_cselect_b32 s43, s27, s39
	s_cselect_b32 s42, s88, s38
	s_cselect_b32 s39, s25, s95
	s_cselect_b32 s38, s92, s94
	v_lshl_add_u64 v[210:211], s[34:35], 0, v[150:151]
	s_add_i32 m0, s11, 0xc000
	ds_read_b128 v[178:181], v159
	ds_read_b128 v[182:185], v159 offset:1024
	ds_read_b128 v[186:189], v159 offset:2048
	ds_read_b128 v[190:193], v159 offset:3072
	ds_read_b128 v[194:197], v159 offset:4096
	ds_read_b128 v[198:201], v159 offset:5120
	ds_read_b128 v[202:205], v159 offset:6144
	ds_read_b128 v[206:209], v159 offset:7168
	global_load_lds_dwordx4 v[210:211], off
	v_lshl_add_u64 v[210:211], s[34:35], 0, v[152:153]
	s_add_i32 m0, s11, 0xe000
	s_nop 0
	global_load_lds_dwordx4 v[210:211], off
	s_waitcnt lgkmcnt(8)
	s_barrier
	s_waitcnt lgkmcnt(0)
	s_setprio 1
	s_waitcnt lgkmcnt(0)
	v_mfma_f32_16x16x32_f16 v[124:127], v[162:165], v[178:181], v[124:127]
	v_mfma_f32_16x16x32_f16 v[120:123], v[170:173], v[178:181], v[120:123]
	v_mfma_f32_16x16x32_f16 v[116:119], v[162:165], v[186:189], v[116:119]
	v_mfma_f32_16x16x32_f16 v[112:115], v[170:173], v[186:189], v[112:115]
	v_mfma_f32_16x16x32_f16 v[100:103], v[162:165], v[194:197], v[100:103]
	v_mfma_f32_16x16x32_f16 v[96:99], v[170:173], v[194:197], v[96:99]
	v_mfma_f32_16x16x32_f16 v[84:87], v[162:165], v[202:205], v[84:87]
	v_mfma_f32_16x16x32_f16 v[80:83], v[170:173], v[202:205], v[80:83]
	v_mfma_f32_16x16x32_f16 v[124:127], v[166:169], v[182:185], v[124:127]
	v_mfma_f32_16x16x32_f16 v[120:123], v[174:177], v[182:185], v[120:123]
	v_mfma_f32_16x16x32_f16 v[116:119], v[166:169], v[190:193], v[116:119]
	v_mfma_f32_16x16x32_f16 v[112:115], v[174:177], v[190:193], v[112:115]
	v_mfma_f32_16x16x32_f16 v[100:103], v[166:169], v[198:201], v[100:103]
	v_mfma_f32_16x16x32_f16 v[96:99], v[174:177], v[198:201], v[96:99]
	v_mfma_f32_16x16x32_f16 v[84:87], v[166:169], v[206:209], v[84:87]
	v_mfma_f32_16x16x32_f16 v[80:83], v[174:177], v[206:209], v[80:83]
	s_setprio 0
	s_barrier
	s_add_i32 s80, s60, s45
	v_lshl_add_u64 v[222:223], s[38:39], 0, v[128:129]
	s_mov_b32 m0, s80
	ds_read_b128 v[210:213], v160
	ds_read_b128 v[214:217], v160 offset:1024
	ds_read_b128 v[218:221], v160 offset:2048
	ds_read_b128 v[228:231], v160 offset:3072
	global_load_lds_dwordx4 v[222:223], off
	v_lshl_add_u64 v[232:233], s[38:39], 0, v[138:139]
	s_add_i32 m0, s80, 0x2000
	s_nop 0
	global_load_lds_dwordx4 v[232:233], off
	s_barrier
	s_waitcnt lgkmcnt(0)
	s_setprio 1
	s_waitcnt lgkmcnt(0)
	v_mfma_f32_16x16x32_f16 v[108:111], v[210:213], v[178:181], v[108:111]
	v_mfma_f32_16x16x32_f16 v[104:107], v[218:221], v[178:181], v[104:107]
	v_mfma_f32_16x16x32_f16 v[92:95], v[210:213], v[186:189], v[92:95]
	v_mfma_f32_16x16x32_f16 v[88:91], v[218:221], v[186:189], v[88:91]
	v_mfma_f32_16x16x32_f16 v[76:79], v[210:213], v[194:197], v[76:79]
	v_mfma_f32_16x16x32_f16 v[72:75], v[218:221], v[194:197], v[72:75]
	v_mfma_f32_16x16x32_f16 v[68:71], v[210:213], v[202:205], v[68:71]
	v_mfma_f32_16x16x32_f16 v[64:67], v[218:221], v[202:205], v[64:67]
	v_mfma_f32_16x16x32_f16 v[108:111], v[214:217], v[182:185], v[108:111]
	v_mfma_f32_16x16x32_f16 v[104:107], v[228:231], v[182:185], v[104:107]
	v_mfma_f32_16x16x32_f16 v[92:95], v[214:217], v[190:193], v[92:95]
	v_mfma_f32_16x16x32_f16 v[88:91], v[228:231], v[190:193], v[88:91]
	v_mfma_f32_16x16x32_f16 v[76:79], v[214:217], v[198:201], v[76:79]
	v_mfma_f32_16x16x32_f16 v[72:75], v[228:231], v[198:201], v[72:75]
	v_mfma_f32_16x16x32_f16 v[68:71], v[214:217], v[206:209], v[68:71]
	v_mfma_f32_16x16x32_f16 v[64:67], v[228:231], v[206:209], v[64:67]
	s_setprio 0
	s_mov_b32 m0, s11
	v_lshl_add_u64 v[234:235], s[42:43], 0, v[144:145]
	s_barrier
	ds_read_b128 v[178:181], v159 offset:16384
	ds_read_b128 v[182:185], v159 offset:17408
	ds_read_b128 v[186:189], v159 offset:18432
	ds_read_b128 v[190:193], v159 offset:19456
	ds_read_b128 v[194:197], v159 offset:20480
	ds_read_b128 v[198:201], v159 offset:21504
	ds_read_b128 v[202:205], v159 offset:22528
	ds_read_b128 v[206:209], v159 offset:23552
	global_load_lds_dwordx4 v[234:235], off
	v_lshl_add_u64 v[236:237], s[42:43], 0, v[140:141]
	s_mov_b32 m0, s53
	s_nop 0
	global_load_lds_dwordx4 v[236:237], off
	s_barrier
	s_waitcnt lgkmcnt(0)
	s_setprio 1
	s_waitcnt lgkmcnt(0)
	v_mfma_f32_16x16x32_f16 v[60:63], v[162:165], v[178:181], v[60:63]
	v_mfma_f32_16x16x32_f16 v[56:59], v[170:173], v[178:181], v[56:59]
	v_mfma_f32_16x16x32_f16 v[52:55], v[162:165], v[186:189], v[52:55]
	v_mfma_f32_16x16x32_f16 v[48:51], v[170:173], v[186:189], v[48:51]
	v_mfma_f32_16x16x32_f16 v[36:39], v[162:165], v[194:197], v[36:39]
	v_mfma_f32_16x16x32_f16 v[32:35], v[170:173], v[194:197], v[32:35]
	v_mfma_f32_16x16x32_f16 v[20:23], v[162:165], v[202:205], v[20:23]
	v_mfma_f32_16x16x32_f16 v[16:19], v[170:173], v[202:205], v[16:19]
	v_mfma_f32_16x16x32_f16 v[60:63], v[166:169], v[182:185], v[60:63]
	v_mfma_f32_16x16x32_f16 v[56:59], v[174:177], v[182:185], v[56:59]
	v_mfma_f32_16x16x32_f16 v[52:55], v[166:169], v[190:193], v[52:55]
	v_mfma_f32_16x16x32_f16 v[48:51], v[174:177], v[190:193], v[48:51]
	v_mfma_f32_16x16x32_f16 v[36:39], v[166:169], v[198:201], v[36:39]
	v_mfma_f32_16x16x32_f16 v[32:35], v[174:177], v[198:201], v[32:35]
	v_mfma_f32_16x16x32_f16 v[20:23], v[166:169], v[206:209], v[20:23]
	v_mfma_f32_16x16x32_f16 v[16:19], v[174:177], v[206:209], v[16:19]
	s_setprio 0
	s_barrier
; #define PG8_STAGE(bufoff, gbase, voff) do { _Pragma("unroll") for (int _i = 0; _i < 2; ++_i) \
;         __builtin_amdgcn_global_load_lds((const unsigned*)((const char*)(gbase) + (voff)[_i]), (LAS unsigned*)(lds + (bufoff) + ldsw + _i * 8192), 16, 0, 0); } while (0)
; #define PG8_LDA(dst, b, h) do { _Pragma("unroll") for (int m = 0; m < 4; ++m) _Pragma("unroll") for (int k = 0; k < 2; ++k) dst[m][k] = *(const LAS h16x8*)(lds + PG8_SA(b, h) + aoff + m * 2048 + k * 1024); } while (0)
; #define PG8_LDB(dst, b, h) do { _Pragma("unroll") for (int n = 0; n < 2; ++n) _Pragma("unroll") for (int k = 0; k < 2; ++k) dst[n][k] = *(const LAS h16x8*)(lds + PG8_SB(b, h) + boff + n * 2048 + k * 1024); } while (0)
; #define PG8_MMA(ai, bj, At, Bt) do { __builtin_amdgcn_s_setprio(1); _Pragma("unroll") for (int m = 0; m < 4; ++m) _Pragma("unroll") for (int n = 0; n < 2; ++n) _Pragma("unroll") for (int k = 0; k < 2; ++k) \
;         acc[ai][bj][m][n] = __builtin_amdgcn_mfma_f32_16x16x32_f16(Bt[n][k], At[m][k], acc[ai][bj][m][n], 0, 0, 0); __builtin_amdgcn_s_setprio(0); } while (0)
; #define PG8_WAIT_V(n) asm volatile("s_waitcnt vmcnt(" #n ")" ::: "memory")
; #define PG8_WAIT_L(n) asm volatile("s_waitcnt lgkmcnt(" #n ")" ::: "memory")
; #define PG8_BAR __builtin_amdgcn_s_barrier()
; #define PG8_SCHED __builtin_amdgcn_sched_barrier(0)
; template <class Epi>
; __device__ __forceinline__ void gemm_phase(LAS unsigned char* lds, const Gemm g, const StaticOrder& S, const Epi& E) {
;     ...
;             PG8_STAGE(PG8_SB(0, 1), b2 + hstep, voffB);
;             PG8_WAIT_V(6); PG8_BAR; PG8_MMA(1, 1, At, B1); PG8_BAR;
;             PG8_LDB(B0, 1, 0); PG8_SCHED; PG8_LDA(At, 1, 0); PG8_STAGE(PG8_SA(0, 1), a2 + hstep, voffA);
;             PG8_WAIT_L(8); PG8_BAR; PG8_WAIT_L(0); PG8_MMA(0, 0, At, B0); PG8_BAR; PG8_SCHED;
;             PG8_LDB(B1, 1, 1); PG8_STAGE(PG8_SB(1, 0), b3, voffB);
;             PG8_BAR; PG8_WAIT_L(0); PG8_MMA(0, 1, At, B1); PG8_BAR;
;             PG8_LDA(At, 1, 1); PG8_STAGE(PG8_SA(1, 0), a3, voffA);
	s_add_u32 vcc_lo, s38, 0x40000
	s_addc_u32 vcc_hi, s39, 0
	s_add_i32 s80, s61, s45
	v_lshl_add_u64 v[162:163], vcc, 0, v[128:129]
	s_mov_b32 m0, s80
	s_nop 0
	global_load_lds_dwordx4 v[162:163], off
	v_lshl_add_u64 v[162:163], vcc, 0, v[138:139]
	s_add_i32 m0, s80, 0x2000
	s_nop 0
	global_load_lds_dwordx4 v[162:163], off
	s_waitcnt vmcnt(6)
	s_barrier
	s_setprio 1
	v_mfma_f32_16x16x32_f16 v[44:47], v[210:213], v[178:181], v[44:47]
	v_mfma_f32_16x16x32_f16 v[40:43], v[218:221], v[178:181], v[40:43]
	v_mfma_f32_16x16x32_f16 v[28:31], v[210:213], v[186:189], v[28:31]
	v_mfma_f32_16x16x32_f16 v[24:27], v[218:221], v[186:189], v[24:27]
	v_mfma_f32_16x16x32_f16 v[12:15], v[210:213], v[194:197], v[12:15]
	v_mfma_f32_16x16x32_f16 v[8:11], v[218:221], v[194:197], v[8:11]
	v_mfma_f32_16x16x32_f16 v[4:7], v[210:213], v[202:205], v[4:7]
	v_mfma_f32_16x16x32_f16 v[0:3], v[218:221], v[202:205], v[0:3]
	v_mfma_f32_16x16x32_f16 v[44:47], v[214:217], v[182:185], v[44:47]
	v_mfma_f32_16x16x32_f16 v[40:43], v[228:231], v[182:185], v[40:43]
	v_mfma_f32_16x16x32_f16 v[28:31], v[214:217], v[190:193], v[28:31]
	v_mfma_f32_16x16x32_f16 v[24:27], v[228:231], v[190:193], v[24:27]
	v_mfma_f32_16x16x32_f16 v[12:15], v[214:217], v[198:201], v[12:15]
	v_mfma_f32_16x16x32_f16 v[8:11], v[228:231], v[198:201], v[8:11]
	v_mfma_f32_16x16x32_f16 v[4:7], v[214:217], v[206:209], v[4:7]
	v_mfma_f32_16x16x32_f16 v[0:3], v[228:231], v[206:209], v[0:3]
	s_setprio 0
	s_add_i32 s80, 0, 0x18000
	v_add_u32_e32 v161, s80, v137
	s_barrier
	ds_read_b128 v[162:165], v161
	ds_read_b128 v[166:169], v161 offset:1024
	ds_read_b128 v[170:173], v161 offset:2048
	ds_read_b128 v[174:177], v161 offset:3072
	s_add_u32 s42, s42, 0x40000
	s_addc_u32 s43, s43, 0
	s_mov_b32 m0, s54
	v_lshl_add_u64 v[210:211], s[42:43], 0, v[144:145]
	ds_read_b128 v[178:181], v159 offset:32768
	ds_read_b128 v[182:185], v159 offset:33792
	ds_read_b128 v[186:189], v159 offset:34816
	ds_read_b128 v[190:193], v159 offset:35840
	ds_read_b128 v[194:197], v159 offset:36864
	ds_read_b128 v[198:201], v159 offset:37888
	ds_read_b128 v[202:205], v159 offset:38912
	ds_read_b128 v[206:209], v159 offset:39936
	global_load_lds_dwordx4 v[210:211], off
	v_lshl_add_u64 v[210:211], s[42:43], 0, v[140:141]
	s_mov_b32 m0, s55
	s_nop 0
	global_load_lds_dwordx4 v[210:211], off
	s_waitcnt lgkmcnt(8)
	s_barrier
	s_waitcnt lgkmcnt(0)
	s_setprio 1
	s_waitcnt lgkmcnt(0)
	v_mfma_f32_16x16x32_f16 v[124:127], v[162:165], v[178:181], v[124:127]
	v_mfma_f32_16x16x32_f16 v[120:123], v[170:173], v[178:181], v[120:123]
	v_mfma_f32_16x16x32_f16 v[116:119], v[162:165], v[186:189], v[116:119]
	v_mfma_f32_16x16x32_f16 v[112:115], v[170:173], v[186:189], v[112:115]
	v_mfma_f32_16x16x32_f16 v[100:103], v[162:165], v[194:197], v[100:103]
	v_mfma_f32_16x16x32_f16 v[96:99], v[170:173], v[194:197], v[96:99]
	v_mfma_f32_16x16x32_f16 v[84:87], v[162:165], v[202:205], v[84:87]
	v_mfma_f32_16x16x32_f16 v[80:83], v[170:173], v[202:205], v[80:83]
	v_mfma_f32_16x16x32_f16 v[124:127], v[166:169], v[182:185], v[124:127]
	v_mfma_f32_16x16x32_f16 v[120:123], v[174:177], v[182:185], v[120:123]
	v_mfma_f32_16x16x32_f16 v[116:119], v[166:169], v[190:193], v[116:119]
	v_mfma_f32_16x16x32_f16 v[112:115], v[174:177], v[190:193], v[112:115]
	v_mfma_f32_16x16x32_f16 v[100:103], v[166:169], v[198:201], v[100:103]
	v_mfma_f32_16x16x32_f16 v[96:99], v[174:177], v[198:201], v[96:99]
	v_mfma_f32_16x16x32_f16 v[84:87], v[166:169], v[206:209], v[84:87]
	v_mfma_f32_16x16x32_f16 v[80:83], v[174:177], v[206:209], v[80:83]
	s_setprio 0
	s_barrier
	s_add_i32 s42, 0, 0x1c000
	s_add_i32 s43, s80, s45
	v_add_u32_e32 v161, s42, v137
	v_lshl_add_u64 v[222:223], v[222:223], 0, s[0:1]
	s_mov_b32 m0, s43
	ds_read_b128 v[210:213], v161
	ds_read_b128 v[214:217], v161 offset:1024
	ds_read_b128 v[218:221], v161 offset:2048
	ds_read_b128 v[228:231], v161 offset:3072
	global_load_lds_dwordx4 v[222:223], off
	v_lshl_add_u64 v[222:223], v[232:233], 0, s[0:1]
	s_add_i32 m0, s43, 0x2000
	s_nop 0
	global_load_lds_dwordx4 v[222:223], off
	s_barrier
	s_waitcnt lgkmcnt(0)
	s_setprio 1
	s_waitcnt lgkmcnt(0)
	v_mfma_f32_16x16x32_f16 v[108:111], v[210:213], v[178:181], v[108:111]
	v_mfma_f32_16x16x32_f16 v[104:107], v[218:221], v[178:181], v[104:107]
	v_mfma_f32_16x16x32_f16 v[92:95], v[210:213], v[186:189], v[92:95]
	v_mfma_f32_16x16x32_f16 v[88:91], v[218:221], v[186:189], v[88:91]
	v_mfma_f32_16x16x32_f16 v[76:79], v[210:213], v[194:197], v[76:79]
	v_mfma_f32_16x16x32_f16 v[72:75], v[218:221], v[194:197], v[72:75]
	v_mfma_f32_16x16x32_f16 v[68:71], v[210:213], v[202:205], v[68:71]
	v_mfma_f32_16x16x32_f16 v[64:67], v[218:221], v[202:205], v[64:67]
	v_mfma_f32_16x16x32_f16 v[108:111], v[214:217], v[182:185], v[108:111]
	v_mfma_f32_16x16x32_f16 v[104:107], v[228:231], v[182:185], v[104:107]
	v_mfma_f32_16x16x32_f16 v[92:95], v[214:217], v[190:193], v[92:95]
	v_mfma_f32_16x16x32_f16 v[88:91], v[228:231], v[190:193], v[88:91]
	v_mfma_f32_16x16x32_f16 v[76:79], v[214:217], v[198:201], v[76:79]
	v_mfma_f32_16x16x32_f16 v[72:75], v[228:231], v[198:201], v[72:75]
	v_mfma_f32_16x16x32_f16 v[68:71], v[214:217], v[206:209], v[68:71]
	v_mfma_f32_16x16x32_f16 v[64:67], v[228:231], v[206:209], v[64:67]
	s_setprio 0
	s_mov_b32 m0, s56
	v_lshl_add_u64 v[222:223], v[234:235], 0, s[0:1]
	s_barrier
	ds_read_b128 v[178:181], v159 offset:49152
	ds_read_b128 v[182:185], v159 offset:50176
	ds_read_b128 v[186:189], v159 offset:51200
	ds_read_b128 v[190:193], v159 offset:52224
	ds_read_b128 v[194:197], v159 offset:53248
	ds_read_b128 v[198:201], v159 offset:54272
	ds_read_b128 v[202:205], v159 offset:55296
	ds_read_b128 v[206:209], v159 offset:56320
	global_load_lds_dwordx4 v[222:223], off
	v_lshl_add_u64 v[222:223], v[236:237], 0, s[0:1]
	s_mov_b32 m0, s57
	s_nop 0
	global_load_lds_dwordx4 v[222:223], off
	s_barrier
; #define PG8_STAGE(bufoff, gbase, voff) do { _Pragma("unroll") for (int _i = 0; _i < 2; ++_i) \
;         __builtin_amdgcn_global_load_lds((const unsigned*)((const char*)(gbase) + (voff)[_i]), (LAS unsigned*)(lds + (bufoff) + ldsw + _i * 8192), 16, 0, 0); } while (0)
; #define PG8_MMA(ai, bj, At, Bt) do { __builtin_amdgcn_s_setprio(1); _Pragma("unroll") for (int m = 0; m < 4; ++m) _Pragma("unroll") for (int n = 0; n < 2; ++n) _Pragma("unroll") for (int k = 0; k < 2; ++k) \
;         acc[ai][bj][m][n] = __builtin_amdgcn_mfma_f32_16x16x32_f16(Bt[n][k], At[m][k], acc[ai][bj][m][n], 0, 0, 0); __builtin_amdgcn_s_setprio(0); } while (0)
; #define PG8_WAIT_V(n) asm volatile("s_waitcnt vmcnt(" #n ")" ::: "memory")
; #define PG8_WAIT_L(n) asm volatile("s_waitcnt lgkmcnt(" #n ")" ::: "memory")
; #define PG8_BAR __builtin_amdgcn_s_barrier()
; #define PG8_SCHED __builtin_amdgcn_sched_barrier(0)
; template <class Epi>
; __device__ __forceinline__ void gemm_phase(LAS unsigned char* lds, const Gemm g, const StaticOrder& S, const Epi& E) {
;     ...
;             PG8_BAR; PG8_WAIT_L(0); PG8_MMA(1, 0, At, B0); PG8_BAR; PG8_SCHED;
;             PG8_STAGE(PG8_SB(1, 1), b3 + hstep, voffB);
;             PG8_WAIT_V(6); PG8_BAR; PG8_MMA(1, 1, At, B1); PG8_BAR;
	s_waitcnt lgkmcnt(0)
	s_setprio 1
	s_waitcnt lgkmcnt(0)
	v_mfma_f32_16x16x32_f16 v[60:63], v[162:165], v[178:181], v[60:63]
	v_mfma_f32_16x16x32_f16 v[56:59], v[170:173], v[178:181], v[56:59]
	v_mfma_f32_16x16x32_f16 v[52:55], v[162:165], v[186:189], v[52:55]
	v_mfma_f32_16x16x32_f16 v[48:51], v[170:173], v[186:189], v[48:51]
	v_mfma_f32_16x16x32_f16 v[36:39], v[162:165], v[194:197], v[36:39]
	v_mfma_f32_16x16x32_f16 v[32:35], v[170:173], v[194:197], v[32:35]
	v_mfma_f32_16x16x32_f16 v[20:23], v[162:165], v[202:205], v[20:23]
	v_mfma_f32_16x16x32_f16 v[16:19], v[170:173], v[202:205], v[16:19]
	v_mfma_f32_16x16x32_f16 v[60:63], v[166:169], v[182:185], v[60:63]
	v_mfma_f32_16x16x32_f16 v[56:59], v[174:177], v[182:185], v[56:59]
	v_mfma_f32_16x16x32_f16 v[52:55], v[166:169], v[190:193], v[52:55]
	v_mfma_f32_16x16x32_f16 v[48:51], v[174:177], v[190:193], v[48:51]
	v_mfma_f32_16x16x32_f16 v[36:39], v[166:169], v[198:201], v[36:39]
	v_mfma_f32_16x16x32_f16 v[32:35], v[174:177], v[198:201], v[32:35]
	v_mfma_f32_16x16x32_f16 v[20:23], v[166:169], v[206:209], v[20:23]
	v_mfma_f32_16x16x32_f16 v[16:19], v[174:177], v[206:209], v[16:19]
	s_setprio 0
	s_barrier
	s_add_u32 s38, s38, 0x40080
	s_addc_u32 s39, s39, 0
	s_add_i32 s42, s42, s45
	v_lshl_add_u64 v[162:163], s[38:39], 0, v[128:129]
	s_mov_b32 m0, s42
	s_nop 0
	global_load_lds_dwordx4 v[162:163], off
	v_lshl_add_u64 v[162:163], s[38:39], 0, v[138:139]
	s_add_i32 m0, s42, 0x2000
	s_nop 0
	global_load_lds_dwordx4 v[162:163], off
	s_waitcnt vmcnt(6)
	s_barrier
	s_setprio 1
	v_mfma_f32_16x16x32_f16 v[44:47], v[210:213], v[178:181], v[44:47]
	v_mfma_f32_16x16x32_f16 v[40:43], v[218:221], v[178:181], v[40:43]
	v_mfma_f32_16x16x32_f16 v[28:31], v[210:213], v[186:189], v[28:31]
	v_mfma_f32_16x16x32_f16 v[24:27], v[218:221], v[186:189], v[24:27]
	v_mfma_f32_16x16x32_f16 v[12:15], v[210:213], v[194:197], v[12:15]
	v_mfma_f32_16x16x32_f16 v[8:11], v[218:221], v[194:197], v[8:11]
	v_mfma_f32_16x16x32_f16 v[4:7], v[210:213], v[202:205], v[4:7]
	v_mfma_f32_16x16x32_f16 v[0:3], v[218:221], v[202:205], v[0:3]
	v_mfma_f32_16x16x32_f16 v[44:47], v[214:217], v[182:185], v[44:47]
	v_mfma_f32_16x16x32_f16 v[40:43], v[228:231], v[182:185], v[40:43]
	v_mfma_f32_16x16x32_f16 v[28:31], v[214:217], v[190:193], v[28:31]
	v_mfma_f32_16x16x32_f16 v[24:27], v[228:231], v[190:193], v[24:27]
	v_mfma_f32_16x16x32_f16 v[12:15], v[214:217], v[198:201], v[12:15]
	v_mfma_f32_16x16x32_f16 v[8:11], v[228:231], v[198:201], v[8:11]
	v_mfma_f32_16x16x32_f16 v[4:7], v[214:217], v[206:209], v[4:7]
	v_mfma_f32_16x16x32_f16 v[0:3], v[228:231], v[206:209], v[0:3]
	s_setprio 0
	s_add_i32 s96, s96, 2
	s_add_u32 s34, s34, 0x100
	s_addc_u32 s35, s35, 0
	s_add_u32 s94, s94, 0x100
	s_addc_u32 s95, s95, 0
	s_cmp_gt_u32 s96, 13
	s_barrier
	s_cbranch_scc0 .LBB0_84
;     __device__ __forceinline__ void operator()(const f32x4 (&acc)[2][2][4][2], const pg8::Unit& u, int wr, int wc, int fr, int fq) const {
;         const int row0 = u.pm * 256 + wr * 64 + fr, col0 = u.pn * 256 + wc * 32 + 8 * fq;
; #pragma unroll
;         for (int ai = 0; ai < 2; ++ai)
; #pragma unroll
;             for (int m = 0; m < 4; ++m) {
;                 const int row = row0 + ai * 128 + m * 16;
;                 float ss = 0.f, rstd = 1.f;
;                 if (MODE == 2) rstd = rsqrtf(rowss[row] * (1.f / 1024.f) + EPS);
; #pragma unroll
;                 for (int bj = 0; bj < 2; ++bj) {
;                     const int c = col0 + bj * 128;
;                     f32x4 v0 = acc[ai][bj][m][0], v1 = acc[ai][bj][m][1];
;                     if (MODE == 1) {
;                         const float* rp = res + (size_t)row * ldres + c;
;                         v0 += *(const f32x4*)rp; v1 += *(const f32x4*)(rp + 4);
;                     }
;                     if (MODE == 3) {
;                         const h16x8 r8 = *(const h16x8*)(res16 + (size_t)row * ldres + c);
; #pragma unroll
;                         for (int j = 0; j < 4; ++j) { v0[j] += (float)r8[j]; v1[j] += (float)r8[4 + j]; }
;                     }
;                     if (MODE == 1 || MODE == 3) {
;                         ss += v0[0] * v0[0] + v0[1] * v0[1] + v0[2] * v0[2] + v0[3] * v0[3] + v1[0] * v1[0] + v1[1] * v1[1] + v1[2] * v1[2] + v1[3] * v1[3];
;                     }
;                     if (MODE == 2) {
; #pragma unroll
;                         for (int j = 0; j < 4; ++j) { float a = fmaxf(v0[j] * rstd, 0.f), b = fmaxf(v1[j] * rstd, 0.f); v0[j] = a * a; v1[j] = b * b; }
;                     }
;                     *(h16x8*)(o16 + (size_t)row * ld16 + c) = pack8(v0, v1);
;                 }
	v_lshl_add_u32 v161, s10, 8, v135
	v_lshl_or_b32 v162, s63, 8, v143
	v_cvt_pk_f16_f32 v123, v122, v123
	v_cvt_pk_f16_f32 v122, v120, v121
	v_cvt_pk_f16_f32 v120, v124, v125
	v_mov_b64_e32 v[124:125], s[90:91]
	v_ashrrev_i32_e32 v163, 31, v162
	v_cvt_pk_f16_f32 v75, v74, v75
	v_cvt_pk_f16_f32 v74, v72, v73
	v_cvt_pk_f16_f32 v72, v76, v77
	v_or_b32_e32 v76, 48, v161
	v_lshlrev_b64 v[162:163], 1, v[162:163]
	v_mad_i64_i32 v[76:77], s[34:35], v76, s62, v[124:125]
	v_lshl_add_u64 v[76:77], v[76:77], 0, v[162:163]
	v_cvt_pk_f16_f32 v67, v66, v67
	v_cvt_pk_f16_f32 v66, v64, v65
	v_cvt_pk_f16_f32 v65, v70, v71
	v_cvt_pk_f16_f32 v64, v68, v69
	v_cvt_pk_f16_f32 v107, v106, v107
	v_cvt_pk_f16_f32 v106, v104, v105
	v_cvt_pk_f16_f32 v104, v108, v109
	v_or_b32_e32 v108, 16, v161
	v_cvt_pk_f16_f32 v91, v90, v91
	v_cvt_pk_f16_f32 v90, v88, v89
	v_cvt_pk_f16_f32 v88, v92, v93
	v_or_b32_e32 v92, 32, v161
	global_store_dwordx4 v[76:77], v[64:67], off offset:256 sc0 sc1
	v_cvt_pk_f16_f32 v43, v42, v43
	v_cvt_pk_f16_f32 v42, v40, v41
	v_add_u32_e32 v64, 0x80, v161
	v_cvt_pk_f16_f32 v40, v44, v45
	v_add_u32_e32 v44, 0x90, v161
	v_cvt_pk_f16_f32 v27, v26, v27
	v_cvt_pk_f16_f32 v26, v24, v25
	v_cvt_pk_f16_f32 v24, v28, v29
	v_add_u32_e32 v28, 0xa0, v161
	v_cvt_pk_f16_f32 v121, v126, v127
	v_mad_i64_i32 v[126:127], s[34:35], v161, s62, v[124:125]
	v_mad_i64_i32 v[108:109], s[34:35], v108, s62, v[124:125]
	v_mad_i64_i32 v[92:93], s[34:35], v92, s62, v[124:125]
	v_cvt_pk_f16_f32 v59, v58, v59
	v_cvt_pk_f16_f32 v58, v56, v57
	v_cvt_pk_f16_f32 v56, v60, v61
	v_mad_i64_i32 v[60:61], s[34:35], v64, s62, v[124:125]
	v_mad_i64_i32 v[44:45], s[34:35], v44, s62, v[124:125]
	v_mad_i64_i32 v[28:29], s[34:35], v28, s62, v[124:125]
	v_cvt_pk_f16_f32 v11, v10, v11
	v_cvt_pk_f16_f32 v10, v8, v9
	v_cvt_pk_f16_f32 v8, v12, v13
	v_add_u32_e32 v12, 0xb0, v161
	v_lshl_add_u64 v[126:127], v[126:127], 0, v[162:163]
	v_cvt_pk_f16_f32 v105, v110, v111
	v_lshl_add_u64 v[108:109], v[108:109], 0, v[162:163]
	v_cvt_pk_f16_f32 v89, v94, v95
	v_lshl_add_u64 v[92:93], v[92:93], 0, v[162:163]
	v_cvt_pk_f16_f32 v73, v78, v79
	v_lshl_add_u64 v[60:61], v[60:61], 0, v[162:163]
	v_cvt_pk_f16_f32 v41, v46, v47
	v_lshl_add_u64 v[44:45], v[44:45], 0, v[162:163]
	v_cvt_pk_f16_f32 v25, v30, v31
	v_lshl_add_u64 v[28:29], v[28:29], 0, v[162:163]
	v_cvt_pk_f16_f32 v9, v14, v15
	v_mad_i64_i32 v[12:13], s[34:35], v12, s62, v[124:125]
	global_store_dwordx4 v[126:127], v[104:107], off offset:256 sc0 sc1
	global_store_dwordx4 v[108:109], v[88:91], off offset:256 sc0 sc1
	global_store_dwordx4 v[92:93], v[72:75], off offset:256 sc0 sc1
	v_cvt_pk_f16_f32 v107, v114, v115
	v_cvt_pk_f16_f32 v106, v112, v113
	v_cvt_pk_f16_f32 v105, v118, v119
	v_cvt_pk_f16_f32 v104, v116, v117
	v_cvt_pk_f16_f32 v91, v98, v99
	v_cvt_pk_f16_f32 v90, v96, v97
	v_cvt_pk_f16_f32 v89, v102, v103
	v_cvt_pk_f16_f32 v88, v100, v101
	v_cvt_pk_f16_f32 v75, v82, v83
	v_cvt_pk_f16_f32 v74, v80, v81
	v_cvt_pk_f16_f32 v73, v86, v87
	v_cvt_pk_f16_f32 v72, v84, v85
	v_cvt_pk_f16_f32 v57, v62, v63
	global_store_dwordx4 v[60:61], v[40:43], off offset:256 sc0 sc1
	global_store_dwordx4 v[44:45], v[24:27], off offset:256 sc0 sc1
	global_store_dwordx4 v[28:29], v[8:11], off offset:256 sc0 sc1
	v_cvt_pk_f16_f32 v43, v50, v51
	v_cvt_pk_f16_f32 v42, v48, v49
	v_cvt_pk_f16_f32 v41, v54, v55
	v_cvt_pk_f16_f32 v40, v52, v53
	v_cvt_pk_f16_f32 v27, v34, v35
	v_cvt_pk_f16_f32 v26, v32, v33
	v_cvt_pk_f16_f32 v25, v38, v39
	v_cvt_pk_f16_f32 v24, v36, v37
	v_cvt_pk_f16_f32 v11, v18, v19
	v_cvt_pk_f16_f32 v10, v16, v17
	v_cvt_pk_f16_f32 v9, v22, v23
	v_cvt_pk_f16_f32 v8, v20, v21
	v_lshl_add_u64 v[12:13], v[12:13], 0, v[162:163]
	v_cvt_pk_f16_f32 v3, v2, v3
	v_cvt_pk_f16_f32 v2, v0, v1
	v_cvt_pk_f16_f32 v1, v6, v7
	v_cvt_pk_f16_f32 v0, v4, v5
	s_and_b64 vcc, exec, s[8:9]
	s_mov_b32 s63, s24
	s_mov_b32 s10, s26
	s_mov_b64 s[38:39], s[30:31]
	s_mov_b64 s[34:35], s[28:29]
	global_store_dwordx4 v[126:127], v[120:123], off sc0 sc1
	global_store_dwordx4 v[108:109], v[104:107], off sc0 sc1
	global_store_dwordx4 v[92:93], v[88:91], off sc0 sc1
	global_store_dwordx4 v[76:77], v[72:75], off sc0 sc1
	global_store_dwordx4 v[60:61], v[56:59], off sc0 sc1
	global_store_dwordx4 v[44:45], v[40:43], off sc0 sc1
	global_store_dwordx4 v[28:29], v[24:27], off sc0 sc1
	global_store_dwordx4 v[12:13], v[8:11], off sc0 sc1
	global_store_dwordx4 v[12:13], v[0:3], off offset:256 sc0 sc1
	s_cbranch_vccz .LBB0_81
	s_waitcnt vmcnt(0)
	s_cmpk_gt_u32 s44, 0xff
	s_cbranch_scc1 .LBB0_88
	s_barrier

; #define PG8_STAGE(bufoff, gbase, voff) do { _Pragma("unroll") for (int _i = 0; _i < 2; ++_i) \
;         __builtin_amdgcn_global_load_lds((const unsigned*)((const char*)(gbase) + (voff)[_i]), (LAS unsigned*)(lds + (bufoff) + ldsw + _i * 8192), 16, 0, 0); } while (0)
; #define PG8_LDA(dst, b, h) do { _Pragma("unroll") for (int m = 0; m < 4; ++m) _Pragma("unroll") for (int k = 0; k < 2; ++k) dst[m][k] = *(const LAS h16x8*)(lds + PG8_SA(b, h) + aoff + m * 2048 + k * 1024); } while (0)
; #define PG8_LDB(dst, b, h) do { _Pragma("unroll") for (int n = 0; n < 2; ++n) _Pragma("unroll") for (int k = 0; k < 2; ++k) dst[n][k] = *(const LAS h16x8*)(lds + PG8_SB(b, h) + boff + n * 2048 + k * 1024); } while (0)
; #define PG8_MMA(ai, bj, At, Bt) do { __builtin_amdgcn_s_setprio(1); _Pragma("unroll") for (int m = 0; m < 4; ++m) _Pragma("unroll") for (int n = 0; n < 2; ++n) _Pragma("unroll") for (int k = 0; k < 2; ++k) \
;         acc[ai][bj][m][n] = __builtin_amdgcn_mfma_f32_16x16x32_f16(Bt[n][k], At[m][k], acc[ai][bj][m][n], 0, 0, 0); __builtin_amdgcn_s_setprio(0); } while (0)
; #define PG8_WAIT_L(n) asm volatile("s_waitcnt lgkmcnt(" #n ")" ::: "memory")
; #define PG8_BAR __builtin_amdgcn_s_barrier()
; #define PG8_SCHED __builtin_amdgcn_sched_barrier(0)
; template <class Epi>
; __device__ __forceinline__ void gemm_phase(LAS unsigned char* lds, const Gemm g, const StaticOrder& S, const Epi& E) {
;     ...
;             PG8_LDB(B0, 0, 0); PG8_SCHED; PG8_LDA(At, 0, 0); PG8_STAGE(PG8_SA(1, 1), a1 + hstep, voffA);
;             PG8_WAIT_L(8); PG8_BAR; PG8_WAIT_L(0); PG8_MMA(0, 0, At, B0); PG8_BAR; PG8_SCHED;
;             PG8_LDB(B1, 0, 1); PG8_STAGE(PG8_SB(0, 0), b2, voffB);
;             PG8_BAR; PG8_WAIT_L(0); PG8_MMA(0, 1, At, B1); PG8_BAR;
;             PG8_LDA(At, 0, 1); PG8_STAGE(PG8_SA(0, 0), a2, voffA);
;             PG8_BAR; PG8_WAIT_L(0); PG8_MMA(1, 0, At, B0); PG8_BAR; PG8_SCHED;
.LBB0_483:
	ds_read_b128 v[160:163], v168
	ds_read_b128 v[164:167], v168 offset:1024
	ds_read_b128 v[172:175], v168 offset:2048
	ds_read_b128 v[176:179], v168 offset:3072
	s_add_u32 s36, s0, 0xfffc0080
	s_addc_u32 s37, s1, -1
	s_cmp_eq_u32 s63, 12
	s_cselect_b32 s39, s27, s37
	s_cselect_b32 s38, s59, s36
	s_cselect_b32 s37, s25, s62
	s_cselect_b32 s36, s60, s61
	v_lshl_add_u64 v[212:213], s[0:1], 0, v[152:153]
	s_add_i32 m0, s35, 0xc000
	ds_read_b128 v[180:183], v169
	ds_read_b128 v[184:187], v169 offset:1024
	ds_read_b128 v[188:191], v169 offset:2048
	ds_read_b128 v[192:195], v169 offset:3072
	ds_read_b128 v[196:199], v169 offset:4096
	ds_read_b128 v[200:203], v169 offset:5120
	ds_read_b128 v[204:207], v169 offset:6144
	ds_read_b128 v[208:211], v169 offset:7168
	global_load_lds_dwordx4 v[212:213], off
	v_lshl_add_u64 v[212:213], s[0:1], 0, v[154:155]
	s_add_i32 m0, s35, 0xe000
	s_nop 0
	global_load_lds_dwordx4 v[212:213], off
	s_waitcnt lgkmcnt(8)
	s_barrier
	s_waitcnt lgkmcnt(0)
	s_setprio 1
	s_waitcnt lgkmcnt(0)
	v_mfma_f32_16x16x32_f16 v[124:127], v[160:163], v[180:183], v[124:127]
	v_mfma_f32_16x16x32_f16 v[120:123], v[172:175], v[180:183], v[120:123]
	v_mfma_f32_16x16x32_f16 v[108:111], v[160:163], v[188:191], v[108:111]
	v_mfma_f32_16x16x32_f16 v[104:107], v[172:175], v[188:191], v[104:107]
	v_mfma_f32_16x16x32_f16 v[92:95], v[160:163], v[196:199], v[92:95]
	v_mfma_f32_16x16x32_f16 v[88:91], v[172:175], v[196:199], v[88:91]
	v_mfma_f32_16x16x32_f16 v[76:79], v[160:163], v[204:207], v[76:79]
	v_mfma_f32_16x16x32_f16 v[72:75], v[172:175], v[204:207], v[72:75]
	v_mfma_f32_16x16x32_f16 v[124:127], v[164:167], v[184:187], v[124:127]
	v_mfma_f32_16x16x32_f16 v[120:123], v[176:179], v[184:187], v[120:123]
	v_mfma_f32_16x16x32_f16 v[108:111], v[164:167], v[192:195], v[108:111]
	v_mfma_f32_16x16x32_f16 v[104:107], v[176:179], v[192:195], v[104:107]
	v_mfma_f32_16x16x32_f16 v[92:95], v[164:167], v[200:203], v[92:95]
	v_mfma_f32_16x16x32_f16 v[88:91], v[176:179], v[200:203], v[88:91]
	v_mfma_f32_16x16x32_f16 v[76:79], v[164:167], v[208:211], v[76:79]
	v_mfma_f32_16x16x32_f16 v[72:75], v[176:179], v[208:211], v[72:75]
	s_setprio 0
	s_barrier
	s_add_i32 s64, s51, s44
	v_lshl_add_u64 v[228:229], s[36:37], 0, v[144:145]
	s_mov_b32 m0, s64
	ds_read_b128 v[212:215], v170
	ds_read_b128 v[216:219], v170 offset:1024
	ds_read_b128 v[220:223], v170 offset:2048
	ds_read_b128 v[224:227], v170 offset:3072
	global_load_lds_dwordx4 v[228:229], off
	v_lshl_add_u64 v[230:231], s[36:37], 0, v[150:151]
	s_add_i32 m0, s64, 0x2000
	s_nop 0
	global_load_lds_dwordx4 v[230:231], off
	s_barrier
	s_waitcnt lgkmcnt(0)
	s_setprio 1
	s_waitcnt lgkmcnt(0)
	v_mfma_f32_16x16x32_f16 v[116:119], v[212:215], v[180:183], v[116:119]
	v_mfma_f32_16x16x32_f16 v[112:115], v[220:223], v[180:183], v[112:115]
	v_mfma_f32_16x16x32_f16 v[100:103], v[212:215], v[188:191], v[100:103]
	v_mfma_f32_16x16x32_f16 v[96:99], v[220:223], v[188:191], v[96:99]
	v_mfma_f32_16x16x32_f16 v[84:87], v[212:215], v[196:199], v[84:87]
	v_mfma_f32_16x16x32_f16 v[80:83], v[220:223], v[196:199], v[80:83]
	v_mfma_f32_16x16x32_f16 v[68:71], v[212:215], v[204:207], v[68:71]
	v_mfma_f32_16x16x32_f16 v[64:67], v[220:223], v[204:207], v[64:67]
	v_mfma_f32_16x16x32_f16 v[116:119], v[216:219], v[184:187], v[116:119]
	v_mfma_f32_16x16x32_f16 v[112:115], v[224:227], v[184:187], v[112:115]
	v_mfma_f32_16x16x32_f16 v[100:103], v[216:219], v[192:195], v[100:103]
	v_mfma_f32_16x16x32_f16 v[96:99], v[224:227], v[192:195], v[96:99]
	v_mfma_f32_16x16x32_f16 v[84:87], v[216:219], v[200:203], v[84:87]
	v_mfma_f32_16x16x32_f16 v[80:83], v[224:227], v[200:203], v[80:83]
	v_mfma_f32_16x16x32_f16 v[68:71], v[216:219], v[208:211], v[68:71]
	v_mfma_f32_16x16x32_f16 v[64:67], v[224:227], v[208:211], v[64:67]
	s_setprio 0
	s_mov_b32 m0, s35
	v_lshl_add_u64 v[232:233], s[38:39], 0, v[142:143]
	s_barrier
	ds_read_b128 v[180:183], v169 offset:16384
	ds_read_b128 v[184:187], v169 offset:17408
	ds_read_b128 v[188:191], v169 offset:18432
	ds_read_b128 v[192:195], v169 offset:19456
	ds_read_b128 v[196:199], v169 offset:20480
	ds_read_b128 v[200:203], v169 offset:21504
	ds_read_b128 v[204:207], v169 offset:22528
	ds_read_b128 v[208:211], v169 offset:23552
	global_load_lds_dwordx4 v[232:233], off
	v_lshl_add_u64 v[234:235], s[38:39], 0, v[148:149]
	s_mov_b32 m0, s45
	s_nop 0
	global_load_lds_dwordx4 v[234:235], off
	s_barrier
	s_waitcnt lgkmcnt(0)
	s_setprio 1
	s_waitcnt lgkmcnt(0)
	v_mfma_f32_16x16x32_f16 v[60:63], v[160:163], v[180:183], v[60:63]
	v_mfma_f32_16x16x32_f16 v[56:59], v[172:175], v[180:183], v[56:59]
	v_mfma_f32_16x16x32_f16 v[44:47], v[160:163], v[188:191], v[44:47]
	v_mfma_f32_16x16x32_f16 v[40:43], v[172:175], v[188:191], v[40:43]
	v_mfma_f32_16x16x32_f16 v[28:31], v[160:163], v[196:199], v[28:31]
	v_mfma_f32_16x16x32_f16 v[24:27], v[172:175], v[196:199], v[24:27]
	v_mfma_f32_16x16x32_f16 v[12:15], v[160:163], v[204:207], v[12:15]
	v_mfma_f32_16x16x32_f16 v[8:11], v[172:175], v[204:207], v[8:11]
	v_mfma_f32_16x16x32_f16 v[60:63], v[164:167], v[184:187], v[60:63]
	v_mfma_f32_16x16x32_f16 v[56:59], v[176:179], v[184:187], v[56:59]
	v_mfma_f32_16x16x32_f16 v[44:47], v[164:167], v[192:195], v[44:47]
	v_mfma_f32_16x16x32_f16 v[40:43], v[176:179], v[192:195], v[40:43]
	v_mfma_f32_16x16x32_f16 v[28:31], v[164:167], v[200:203], v[28:31]
	v_mfma_f32_16x16x32_f16 v[24:27], v[176:179], v[200:203], v[24:27]
	v_mfma_f32_16x16x32_f16 v[12:15], v[164:167], v[208:211], v[12:15]
	v_mfma_f32_16x16x32_f16 v[8:11], v[176:179], v[208:211], v[8:11]
	s_setprio 0
	s_barrier
; #define PG8_STAGE(bufoff, gbase, voff) do { _Pragma("unroll") for (int _i = 0; _i < 2; ++_i) \
;         __builtin_amdgcn_global_load_lds((const unsigned*)((const char*)(gbase) + (voff)[_i]), (LAS unsigned*)(lds + (bufoff) + ldsw + _i * 8192), 16, 0, 0); } while (0)
; #define PG8_LDA(dst, b, h) do { _Pragma("unroll") for (int m = 0; m < 4; ++m) _Pragma("unroll") for (int k = 0; k < 2; ++k) dst[m][k] = *(const LAS h16x8*)(lds + PG8_SA(b, h) + aoff + m * 2048 + k * 1024); } while (0)
; #define PG8_LDB(dst, b, h) do { _Pragma("unroll") for (int n = 0; n < 2; ++n) _Pragma("unroll") for (int k = 0; k < 2; ++k) dst[n][k] = *(const LAS h16x8*)(lds + PG8_SB(b, h) + boff + n * 2048 + k * 1024); } while (0)
; #define PG8_MMA(ai, bj, At, Bt) do { __builtin_amdgcn_s_setprio(1); _Pragma("unroll") for (int m = 0; m < 4; ++m) _Pragma("unroll") for (int n = 0; n < 2; ++n) _Pragma("unroll") for (int k = 0; k < 2; ++k) \
;         acc[ai][bj][m][n] = __builtin_amdgcn_mfma_f32_16x16x32_f16(Bt[n][k], At[m][k], acc[ai][bj][m][n], 0, 0, 0); __builtin_amdgcn_s_setprio(0); } while (0)
; #define PG8_WAIT_V(n) asm volatile("s_waitcnt vmcnt(" #n ")" ::: "memory")
; #define PG8_WAIT_L(n) asm volatile("s_waitcnt lgkmcnt(" #n ")" ::: "memory")
; #define PG8_BAR __builtin_amdgcn_s_barrier()
; #define PG8_SCHED __builtin_amdgcn_sched_barrier(0)
; template <class Epi>
; __device__ __forceinline__ void gemm_phase(LAS unsigned char* lds, const Gemm g, const StaticOrder& S, const Epi& E) {
;     ...
;             PG8_STAGE(PG8_SB(0, 1), b2 + hstep, voffB);
;             PG8_WAIT_V(6); PG8_BAR; PG8_MMA(1, 1, At, B1); PG8_BAR;
;             PG8_LDB(B0, 1, 0); PG8_SCHED; PG8_LDA(At, 1, 0); PG8_STAGE(PG8_SA(0, 1), a2 + hstep, voffA);
;             PG8_WAIT_L(8); PG8_BAR; PG8_WAIT_L(0); PG8_MMA(0, 0, At, B0); PG8_BAR; PG8_SCHED;
;             PG8_LDB(B1, 1, 1); PG8_STAGE(PG8_SB(1, 0), b3, voffB);
;             PG8_BAR; PG8_WAIT_L(0); PG8_MMA(0, 1, At, B1); PG8_BAR;
;             PG8_LDA(At, 1, 1); PG8_STAGE(PG8_SA(1, 0), a3, voffA);
	s_add_u32 s64, s36, 0x40000
	s_addc_u32 s65, s37, 0
	s_add_i32 s66, s52, s44
	v_lshl_add_u64 v[160:161], s[64:65], 0, v[144:145]
	s_mov_b32 m0, s66
	s_nop 0
	global_load_lds_dwordx4 v[160:161], off
	v_lshl_add_u64 v[160:161], s[64:65], 0, v[150:151]
	s_add_i32 m0, s66, 0x2000
	s_nop 0
	global_load_lds_dwordx4 v[160:161], off
	s_waitcnt vmcnt(6)
	s_barrier
	s_setprio 1
	v_mfma_f32_16x16x32_f16 v[52:55], v[212:215], v[180:183], v[52:55]
	v_mfma_f32_16x16x32_f16 v[48:51], v[220:223], v[180:183], v[48:51]
	v_mfma_f32_16x16x32_f16 v[36:39], v[212:215], v[188:191], v[36:39]
	v_mfma_f32_16x16x32_f16 v[32:35], v[220:223], v[188:191], v[32:35]
	v_mfma_f32_16x16x32_f16 v[20:23], v[212:215], v[196:199], v[20:23]
	v_mfma_f32_16x16x32_f16 v[16:19], v[220:223], v[196:199], v[16:19]
	v_mfma_f32_16x16x32_f16 v[4:7], v[212:215], v[204:207], v[4:7]
	v_mfma_f32_16x16x32_f16 v[0:3], v[220:223], v[204:207], v[0:3]
	v_mfma_f32_16x16x32_f16 v[52:55], v[216:219], v[184:187], v[52:55]
	v_mfma_f32_16x16x32_f16 v[48:51], v[224:227], v[184:187], v[48:51]
	v_mfma_f32_16x16x32_f16 v[36:39], v[216:219], v[192:195], v[36:39]
	v_mfma_f32_16x16x32_f16 v[32:35], v[224:227], v[192:195], v[32:35]
	v_mfma_f32_16x16x32_f16 v[20:23], v[216:219], v[200:203], v[20:23]
	v_mfma_f32_16x16x32_f16 v[16:19], v[224:227], v[200:203], v[16:19]
	v_mfma_f32_16x16x32_f16 v[4:7], v[216:219], v[208:211], v[4:7]
	v_mfma_f32_16x16x32_f16 v[0:3], v[224:227], v[208:211], v[0:3]
	s_setprio 0
	s_add_i32 s64, 0, 0x18000
	v_add_u32_e32 v176, s64, v141
	s_barrier
	ds_read_b128 v[160:163], v176
	ds_read_b128 v[164:167], v176 offset:1024
	ds_read_b128 v[172:175], v176 offset:2048
	ds_read_b128 v[176:179], v176 offset:3072
	s_add_u32 s38, s38, 0x40000
	s_addc_u32 s39, s39, 0
	s_mov_b32 m0, s46
	v_lshl_add_u64 v[212:213], s[38:39], 0, v[142:143]
	ds_read_b128 v[180:183], v169 offset:32768
	ds_read_b128 v[184:187], v169 offset:33792
	ds_read_b128 v[188:191], v169 offset:34816
	ds_read_b128 v[192:195], v169 offset:35840
	ds_read_b128 v[196:199], v169 offset:36864
	ds_read_b128 v[200:203], v169 offset:37888
	ds_read_b128 v[204:207], v169 offset:38912
	ds_read_b128 v[208:211], v169 offset:39936
	global_load_lds_dwordx4 v[212:213], off
	v_lshl_add_u64 v[212:213], s[38:39], 0, v[148:149]
	s_mov_b32 m0, s47
	s_nop 0
	global_load_lds_dwordx4 v[212:213], off
	s_waitcnt lgkmcnt(8)
	s_barrier
	s_waitcnt lgkmcnt(0)
	s_setprio 1
	s_waitcnt lgkmcnt(0)
	v_mfma_f32_16x16x32_f16 v[124:127], v[160:163], v[180:183], v[124:127]
	v_mfma_f32_16x16x32_f16 v[120:123], v[172:175], v[180:183], v[120:123]
	v_mfma_f32_16x16x32_f16 v[108:111], v[160:163], v[188:191], v[108:111]
	v_mfma_f32_16x16x32_f16 v[104:107], v[172:175], v[188:191], v[104:107]
	v_mfma_f32_16x16x32_f16 v[92:95], v[160:163], v[196:199], v[92:95]
	v_mfma_f32_16x16x32_f16 v[88:91], v[172:175], v[196:199], v[88:91]
	v_mfma_f32_16x16x32_f16 v[76:79], v[160:163], v[204:207], v[76:79]
	v_mfma_f32_16x16x32_f16 v[72:75], v[172:175], v[204:207], v[72:75]
	v_mfma_f32_16x16x32_f16 v[124:127], v[164:167], v[184:187], v[124:127]
	v_mfma_f32_16x16x32_f16 v[120:123], v[176:179], v[184:187], v[120:123]
	v_mfma_f32_16x16x32_f16 v[108:111], v[164:167], v[192:195], v[108:111]
	v_mfma_f32_16x16x32_f16 v[104:107], v[176:179], v[192:195], v[104:107]
	v_mfma_f32_16x16x32_f16 v[92:95], v[164:167], v[200:203], v[92:95]
	v_mfma_f32_16x16x32_f16 v[88:91], v[176:179], v[200:203], v[88:91]
	v_mfma_f32_16x16x32_f16 v[76:79], v[164:167], v[208:211], v[76:79]
	v_mfma_f32_16x16x32_f16 v[72:75], v[176:179], v[208:211], v[72:75]
	s_setprio 0
	s_barrier
	s_add_i32 s38, 0, 0x1c000
	s_add_i32 s39, s64, s44
	v_add_u32_e32 v224, s38, v141
	v_lshl_add_u64 v[228:229], v[228:229], 0, s[8:9]
	s_mov_b32 m0, s39
	ds_read_b128 v[212:215], v224
	ds_read_b128 v[216:219], v224 offset:1024
	ds_read_b128 v[220:223], v224 offset:2048
	ds_read_b128 v[224:227], v224 offset:3072
	global_load_lds_dwordx4 v[228:229], off
	v_lshl_add_u64 v[228:229], v[230:231], 0, s[8:9]
	s_add_i32 m0, s39, 0x2000
	s_nop 0
	global_load_lds_dwordx4 v[228:229], off
	s_barrier
	s_waitcnt lgkmcnt(0)
	s_setprio 1
	s_waitcnt lgkmcnt(0)
	v_mfma_f32_16x16x32_f16 v[116:119], v[212:215], v[180:183], v[116:119]
	v_mfma_f32_16x16x32_f16 v[112:115], v[220:223], v[180:183], v[112:115]
	v_mfma_f32_16x16x32_f16 v[100:103], v[212:215], v[188:191], v[100:103]
	v_mfma_f32_16x16x32_f16 v[96:99], v[220:223], v[188:191], v[96:99]
	v_mfma_f32_16x16x32_f16 v[84:87], v[212:215], v[196:199], v[84:87]
	v_mfma_f32_16x16x32_f16 v[80:83], v[220:223], v[196:199], v[80:83]
	v_mfma_f32_16x16x32_f16 v[68:71], v[212:215], v[204:207], v[68:71]
	v_mfma_f32_16x16x32_f16 v[64:67], v[220:223], v[204:207], v[64:67]
	v_mfma_f32_16x16x32_f16 v[116:119], v[216:219], v[184:187], v[116:119]
	v_mfma_f32_16x16x32_f16 v[112:115], v[224:227], v[184:187], v[112:115]
	v_mfma_f32_16x16x32_f16 v[100:103], v[216:219], v[192:195], v[100:103]
	v_mfma_f32_16x16x32_f16 v[96:99], v[224:227], v[192:195], v[96:99]
	v_mfma_f32_16x16x32_f16 v[84:87], v[216:219], v[200:203], v[84:87]
	v_mfma_f32_16x16x32_f16 v[80:83], v[224:227], v[200:203], v[80:83]
	v_mfma_f32_16x16x32_f16 v[68:71], v[216:219], v[208:211], v[68:71]
	v_mfma_f32_16x16x32_f16 v[64:67], v[224:227], v[208:211], v[64:67]
	s_setprio 0
	s_mov_b32 m0, s49
	v_lshl_add_u64 v[228:229], v[232:233], 0, s[8:9]
	s_barrier
	ds_read_b128 v[180:183], v169 offset:49152
	ds_read_b128 v[184:187], v169 offset:50176
	ds_read_b128 v[188:191], v169 offset:51200
	ds_read_b128 v[192:195], v169 offset:52224
	ds_read_b128 v[196:199], v169 offset:53248
	ds_read_b128 v[200:203], v169 offset:54272
	ds_read_b128 v[204:207], v169 offset:55296
	ds_read_b128 v[208:211], v169 offset:56320
	global_load_lds_dwordx4 v[228:229], off
	v_lshl_add_u64 v[228:229], v[234:235], 0, s[8:9]
	s_mov_b32 m0, s50
	s_nop 0
	global_load_lds_dwordx4 v[228:229], off
	s_barrier
; #define PG8_STAGE(bufoff, gbase, voff) do { _Pragma("unroll") for (int _i = 0; _i < 2; ++_i) \
;         __builtin_amdgcn_global_load_lds((const unsigned*)((const char*)(gbase) + (voff)[_i]), (LAS unsigned*)(lds + (bufoff) + ldsw + _i * 8192), 16, 0, 0); } while (0)
; #define PG8_WAIT_V(n) asm volatile("s_waitcnt vmcnt(" #n ")" ::: "memory")
; #define PG8_WAIT_L(n) asm volatile("s_waitcnt lgkmcnt(" #n ")" ::: "memory")
; template <class Epi>
; __device__ __forceinline__ void gemm_phase(LAS unsigned char* lds, const Gemm g, const StaticOrder& S, const Epi& E) {
;     ...
;             PG8_BAR; PG8_WAIT_L(0); PG8_MMA(1, 0, At, B0); PG8_BAR; PG8_SCHED;
;             PG8_STAGE(PG8_SB(1, 1), b3 + hstep, voffB);
;             PG8_WAIT_V(6); PG8_BAR; PG8_MMA(1, 1, At, B1); PG8_BAR;
;     __device__ __forceinline__ void operator()(const f32x4 (&acc)[2][2][4][2], const pg8::Unit& u, int wr, int wc, int fr, int fq) const {
;     ...
;                 const int row = row0 + ai * 128 + m * 16;
;                 float ss = 0.f, rstd = 1.f;
;                 if (MODE == 2) rstd = rsqrtf(rowss[row] * (1.f / 1024.f) + EPS);
; #pragma unroll
;                 for (int bj = 0; bj < 2; ++bj) {
;                     const int c = col0 + bj * 128;
;                     f32x4 v0 = acc[ai][bj][m][0], v1 = acc[ai][bj][m][1];
;                     if (MODE == 1) {
;                         const float* rp = res + (size_t)row * ldres + c;
;                         v0 += *(const f32x4*)rp; v1 += *(const f32x4*)(rp + 4);
;                     }
;                     if (MODE == 3) {
;                         const h16x8 r8 = *(const h16x8*)(res16 + (size_t)row * ldres + c);
; #pragma unroll
;                         for (int j = 0; j < 4; ++j) { v0[j] += (float)r8[j]; v1[j] += (float)r8[4 + j]; }
;                     }
;                     if (MODE == 1 || MODE == 3) {
;                         ss += v0[0] * v0[0] + v0[1] * v0[1] + v0[2] * v0[2] + v0[3] * v0[3] + v1[0] * v1[0] + v1[1] * v1[1] + v1[2] * v1[2] + v1[3] * v1[3];
;                     }
;                     if (MODE == 2) {
; #pragma unroll
;                         for (int j = 0; j < 4; ++j) { float a = fmaxf(v0[j] * rstd, 0.f), b = fmaxf(v1[j] * rstd, 0.f); v0[j] = a * a; v1[j] = b * b; }
;                     }
;                     *(h16x8*)(o16 + (size_t)row * ld16 + c) = pack8(v0, v1);
	s_waitcnt lgkmcnt(0)
	s_setprio 1
	s_waitcnt lgkmcnt(0)
	v_mfma_f32_16x16x32_f16 v[60:63], v[160:163], v[180:183], v[60:63]
	v_mfma_f32_16x16x32_f16 v[56:59], v[172:175], v[180:183], v[56:59]
	v_mfma_f32_16x16x32_f16 v[44:47], v[160:163], v[188:191], v[44:47]
	v_mfma_f32_16x16x32_f16 v[40:43], v[172:175], v[188:191], v[40:43]
	v_mfma_f32_16x16x32_f16 v[28:31], v[160:163], v[196:199], v[28:31]
	v_mfma_f32_16x16x32_f16 v[24:27], v[172:175], v[196:199], v[24:27]
	v_mfma_f32_16x16x32_f16 v[12:15], v[160:163], v[204:207], v[12:15]
	v_mfma_f32_16x16x32_f16 v[8:11], v[172:175], v[204:207], v[8:11]
	v_mfma_f32_16x16x32_f16 v[60:63], v[164:167], v[184:187], v[60:63]
	v_mfma_f32_16x16x32_f16 v[56:59], v[176:179], v[184:187], v[56:59]
	v_mfma_f32_16x16x32_f16 v[44:47], v[164:167], v[192:195], v[44:47]
	v_mfma_f32_16x16x32_f16 v[40:43], v[176:179], v[192:195], v[40:43]
	v_mfma_f32_16x16x32_f16 v[28:31], v[164:167], v[200:203], v[28:31]
	v_mfma_f32_16x16x32_f16 v[24:27], v[176:179], v[200:203], v[24:27]
	v_mfma_f32_16x16x32_f16 v[12:15], v[164:167], v[208:211], v[12:15]
	v_mfma_f32_16x16x32_f16 v[8:11], v[176:179], v[208:211], v[8:11]
	s_setprio 0
	s_barrier
	s_add_u32 s36, s36, 0x40080
	s_addc_u32 s37, s37, 0
	s_add_i32 s38, s38, s44
	v_lshl_add_u64 v[160:161], s[36:37], 0, v[144:145]
	s_mov_b32 m0, s38
	s_nop 0
	global_load_lds_dwordx4 v[160:161], off
	v_lshl_add_u64 v[160:161], s[36:37], 0, v[150:151]
	s_add_i32 m0, s38, 0x2000
	s_nop 0
	global_load_lds_dwordx4 v[160:161], off
	s_waitcnt vmcnt(6)
	s_barrier
	s_setprio 1
	v_mfma_f32_16x16x32_f16 v[52:55], v[212:215], v[180:183], v[52:55]
	v_mfma_f32_16x16x32_f16 v[48:51], v[220:223], v[180:183], v[48:51]
	v_mfma_f32_16x16x32_f16 v[36:39], v[212:215], v[188:191], v[36:39]
	v_mfma_f32_16x16x32_f16 v[32:35], v[220:223], v[188:191], v[32:35]
	v_mfma_f32_16x16x32_f16 v[20:23], v[212:215], v[196:199], v[20:23]
	v_mfma_f32_16x16x32_f16 v[16:19], v[220:223], v[196:199], v[16:19]
	v_mfma_f32_16x16x32_f16 v[4:7], v[212:215], v[204:207], v[4:7]
	v_mfma_f32_16x16x32_f16 v[0:3], v[220:223], v[204:207], v[0:3]
	v_mfma_f32_16x16x32_f16 v[52:55], v[216:219], v[184:187], v[52:55]
	v_mfma_f32_16x16x32_f16 v[48:51], v[224:227], v[184:187], v[48:51]
	v_mfma_f32_16x16x32_f16 v[36:39], v[216:219], v[192:195], v[36:39]
	v_mfma_f32_16x16x32_f16 v[32:35], v[224:227], v[192:195], v[32:35]
	v_mfma_f32_16x16x32_f16 v[20:23], v[216:219], v[200:203], v[20:23]
	v_mfma_f32_16x16x32_f16 v[16:19], v[224:227], v[200:203], v[16:19]
	v_mfma_f32_16x16x32_f16 v[4:7], v[216:219], v[208:211], v[4:7]
	v_mfma_f32_16x16x32_f16 v[0:3], v[224:227], v[208:211], v[0:3]
	s_setprio 0
	s_add_i32 s63, s63, 2
	s_add_u32 s0, s0, 0x100
	s_addc_u32 s1, s1, 0
	s_add_u32 s61, s61, 0x100
	s_addc_u32 s62, s62, 0
	s_cmp_gt_u32 s63, 13
	s_barrier
	s_cbranch_scc0 .LBB0_483
	v_lshl_add_u32 v166, s34, 8, v139
	v_ashrrev_i32_e32 v167, 31, v166
	v_lshl_add_u64 v[160:161], v[166:167], 2, s[14:15]
	global_load_dword v176, v[160:161], off
	global_load_dword v182, v[160:161], off offset:64
	global_load_dword v183, v[160:161], off offset:128
	global_load_dword v184, v[160:161], off offset:192
	global_load_dword v185, v[160:161], off offset:512
	global_load_dword v186, v[160:161], off offset:576
	global_load_dword v187, v[160:161], off offset:640
	global_load_dword v188, v[160:161], off offset:704
	v_lshl_or_b32 v162, s58, 8, v147
	v_ashrrev_i32_e32 v163, 31, v162
	v_lshlrev_b64 v[164:165], 1, v[162:163]
	v_lshlrev_b64 v[174:175], 13, v[166:167]
	v_or_b32_e32 v172, 16, v166
	v_ashrrev_i32_e32 v173, 31, v172
	s_mov_b32 s58, s24
	s_mov_b32 s34, s26
	s_mov_b64 s[36:37], s[30:31]
	s_mov_b64 s[38:39], s[28:29]
	s_waitcnt vmcnt(0)
	v_fmamk_f32 v162, v176, 0x3a800000, v171
	v_mul_f32_e32 v163, 0x4b800000, v162
	v_cmp_gt_f32_e32 vcc, s53, v162
	s_nop 1
	v_cndmask_b32_e32 v162, v162, v163, vcc
	v_rsq_f32_e32 v167, v162
	v_lshl_add_u64 v[162:163], s[12:13], 0, v[174:175]
	v_lshl_add_u64 v[162:163], v[162:163], 0, v[164:165]
	v_lshl_add_u64 v[174:175], v[172:173], 2, s[14:15]
	v_mul_f32_e32 v176, 0x45800000, v167
	v_cndmask_b32_e32 v167, v167, v176, vcc
	v_mul_f32_e32 v120, v120, v167
	v_mul_f32_e32 v125, v125, v167
	v_mul_f32_e32 v121, v121, v167
	v_mul_f32_e32 v126, v126, v167
	v_mul_f32_e32 v122, v122, v167
	v_mul_f32_e32 v127, v127, v167
	v_mul_f32_e32 v124, v124, v167
	v_mul_f32_e32 v123, v123, v167
	v_mul_f32_e32 v176, v116, v167
	v_mul_f32_e32 v177, v112, v167
	v_mul_f32_e32 v178, v117, v167
	v_mul_f32_e32 v179, v113, v167
	v_mul_f32_e32 v118, v118, v167
	v_mul_f32_e32 v180, v114, v167
	v_mul_f32_e32 v181, v119, v167
	v_mul_f32_e32 v167, v115, v167
	v_max_f32_e32 v113, 0, v120
	v_max_f32_e32 v114, 0, v125
	v_max_f32_e32 v116, 0, v121
	v_max_f32_e32 v115, 0, v126
	v_max_f32_e32 v117, 0, v122
	v_max_f32_e32 v112, 0, v127
	v_max_f32_e32 v124, 0, v124
	v_max_f32_e32 v125, 0, v123
	v_max_f32_e32 v119, 0, v177
	v_max_f32_e32 v120, 0, v178
	v_max_f32_e32 v122, 0, v179
	v_max_f32_e32 v121, 0, v118
	v_max_f32_e32 v123, 0, v180
	v_max_f32_e32 v118, 0, v181
	v_pk_mul_f32 v[114:115], v[114:115], v[114:115]
	v_pk_mul_f32 v[112:113], v[112:113], v[112:113]
	v_pk_mul_f32 v[116:117], v[116:117], v[116:117]
	v_max_f32_e32 v126, 0, v176
	v_fma_mixlo_f16 v124, v124, v124, 0
	v_pk_mul_f32 v[120:121], v[120:121], v[120:121]
	v_pk_mul_f32 v[118:119], v[118:119], v[118:119]
	v_pk_mul_f32 v[122:123], v[122:123], v[122:123]
	v_cvt_pk_f16_f32 v114, v114, v115
	v_cvt_pk_f16_f32 v115, v112, v113
	v_cvt_pk_f16_f32 v116, v116, v117
	v_fma_mixlo_f16 v126, v126, v126, 0
	v_cvt_pk_f16_f32 v117, v120, v121
	v_cvt_pk_f16_f32 v118, v118, v119
	v_cvt_pk_f16_f32 v119, v122, v123
	v_pack_b32_f16 v112, v124, v114
;     __device__ __forceinline__ void operator()(const f32x4 (&acc)[2][2][4][2], const pg8::Unit& u, int wr, int wc, int fr, int fq) const {
;     ...
;                 const int row = row0 + ai * 128 + m * 16;
;                 float ss = 0.f, rstd = 1.f;
;                 if (MODE == 2) rstd = rsqrtf(rowss[row] * (1.f / 1024.f) + EPS);
; #pragma unroll
;                 for (int bj = 0; bj < 2; ++bj) {
;                     const int c = col0 + bj * 128;
;                     f32x4 v0 = acc[ai][bj][m][0], v1 = acc[ai][bj][m][1];
;                     if (MODE == 1) {
;                         const float* rp = res + (size_t)row * ldres + c;
;                         v0 += *(const f32x4*)rp; v1 += *(const f32x4*)(rp + 4);
;                     }
;                     if (MODE == 3) {
;                         const h16x8 r8 = *(const h16x8*)(res16 + (size_t)row * ldres + c);
; #pragma unroll
;                         for (int j = 0; j < 4; ++j) { v0[j] += (float)r8[j]; v1[j] += (float)r8[4 + j]; }
;                     }
;                     if (MODE == 1 || MODE == 3) {
;                         ss += v0[0] * v0[0] + v0[1] * v0[1] + v0[2] * v0[2] + v0[3] * v0[3] + v1[0] * v1[0] + v1[1] * v1[1] + v1[2] * v1[2] + v1[3] * v1[3];
;                     }
;                     if (MODE == 2) {
; #pragma unroll
;                         for (int j = 0; j < 4; ++j) { float a = fmaxf(v0[j] * rstd, 0.f), b = fmaxf(v1[j] * rstd, 0.f); v0[j] = a * a; v1[j] = b * b; }
;                     }
;                     *(h16x8*)(o16 + (size_t)row * ld16 + c) = pack8(v0, v1);
	v_alignbit_b32 v113, v115, v114, 16
	v_alignbit_b32 v114, v116, v115, 16
	v_lshrrev_b32_e32 v115, 16, v116
	v_max_f32_e32 v127, 0, v167
	v_pack_b32_f16 v116, v126, v117
	v_alignbit_b32 v117, v118, v117, 16
	v_alignbit_b32 v118, v119, v118, 16
	v_lshrrev_b32_e32 v119, 16, v119
	v_fma_mixhi_f16 v115, v125, v125, 0
	v_fma_mixhi_f16 v119, v127, v127, 0
	global_store_dwordx4 v[162:163], v[112:115], off sc0 sc1
	global_store_dwordx4 v[162:163], v[116:119], off offset:256 sc0 sc1
	s_nop 1
	v_mov_b32_e32 v116, v182
	v_lshlrev_b64 v[114:115], 13, v[172:173]
	v_or_b32_e32 v112, 32, v166
	v_lshl_add_u64 v[114:115], s[12:13], 0, v[114:115]
	v_ashrrev_i32_e32 v113, 31, v112
	v_lshl_add_u64 v[114:115], v[114:115], 0, v[164:165]
	s_nop 0
	v_fmamk_f32 v116, v116, 0x3a800000, v171
	v_mul_f32_e32 v117, 0x4b800000, v116
	v_cmp_gt_f32_e32 vcc, s53, v116
	s_nop 1
	v_cndmask_b32_e32 v116, v116, v117, vcc
	v_rsq_f32_e32 v118, v116
	v_lshl_add_u64 v[116:117], v[112:113], 2, s[14:15]
	v_mul_f32_e32 v119, 0x45800000, v118
	v_cndmask_b32_e32 v118, v118, v119, vcc
	v_mul_f32_e32 v104, v104, v118
	v_mul_f32_e32 v109, v109, v118
	v_mul_f32_e32 v105, v105, v118
	v_mul_f32_e32 v110, v110, v118
	v_mul_f32_e32 v106, v106, v118
	v_mul_f32_e32 v111, v111, v118
	v_mul_f32_e32 v108, v108, v118
	v_mul_f32_e32 v107, v107, v118
	v_mul_f32_e32 v119, v100, v118
	v_mul_f32_e32 v120, v96, v118
	v_mul_f32_e32 v121, v101, v118
	v_mul_f32_e32 v122, v97, v118
	v_mul_f32_e32 v102, v102, v118
	v_mul_f32_e32 v123, v98, v118
	v_mul_f32_e32 v124, v103, v118
	v_mul_f32_e32 v118, v99, v118
	v_max_f32_e32 v97, 0, v104
	v_max_f32_e32 v98, 0, v109
	v_max_f32_e32 v100, 0, v105
	v_max_f32_e32 v99, 0, v110
	v_max_f32_e32 v101, 0, v106
	v_max_f32_e32 v96, 0, v111
	v_max_f32_e32 v108, 0, v108
	v_max_f32_e32 v109, 0, v107
	v_max_f32_e32 v103, 0, v120
	v_max_f32_e32 v104, 0, v121
	v_max_f32_e32 v106, 0, v122
	v_max_f32_e32 v105, 0, v102
	v_max_f32_e32 v107, 0, v123
	v_max_f32_e32 v102, 0, v124
	v_pk_mul_f32 v[98:99], v[98:99], v[98:99]
	v_pk_mul_f32 v[96:97], v[96:97], v[96:97]
	v_pk_mul_f32 v[100:101], v[100:101], v[100:101]
	v_max_f32_e32 v110, 0, v119
	v_fma_mixlo_f16 v108, v108, v108, 0
	v_pk_mul_f32 v[104:105], v[104:105], v[104:105]
	v_pk_mul_f32 v[102:103], v[102:103], v[102:103]
	v_pk_mul_f32 v[106:107], v[106:107], v[106:107]
	v_cvt_pk_f16_f32 v98, v98, v99
	v_cvt_pk_f16_f32 v99, v96, v97
	v_cvt_pk_f16_f32 v100, v100, v101
	v_fma_mixlo_f16 v110, v110, v110, 0
	v_cvt_pk_f16_f32 v101, v104, v105
	v_cvt_pk_f16_f32 v102, v102, v103
	v_cvt_pk_f16_f32 v103, v106, v107
	v_pack_b32_f16 v96, v108, v98
	v_alignbit_b32 v97, v99, v98, 16
	v_alignbit_b32 v98, v100, v99, 16
	v_lshrrev_b32_e32 v99, 16, v100
	v_max_f32_e32 v111, 0, v118
	v_pack_b32_f16 v100, v110, v101
	v_alignbit_b32 v101, v102, v101, 16
	v_alignbit_b32 v102, v103, v102, 16
	v_lshrrev_b32_e32 v103, 16, v103
	v_fma_mixhi_f16 v99, v109, v109, 0
	v_fma_mixhi_f16 v103, v111, v111, 0
	global_store_dwordx4 v[114:115], v[96:99], off sc0 sc1
	global_store_dwordx4 v[114:115], v[100:103], off offset:256 sc0 sc1
	s_nop 1
	v_mov_b32_e32 v100, v183
	v_lshlrev_b64 v[98:99], 13, v[112:113]
	v_or_b32_e32 v96, 48, v166
	v_lshl_add_u64 v[98:99], s[12:13], 0, v[98:99]
	v_ashrrev_i32_e32 v97, 31, v96
	v_lshl_add_u64 v[98:99], v[98:99], 0, v[164:165]
	s_nop 0
	v_fmamk_f32 v100, v100, 0x3a800000, v171
	v_mul_f32_e32 v101, 0x4b800000, v100
	v_cmp_gt_f32_e32 vcc, s53, v100
	s_nop 1
	v_cndmask_b32_e32 v100, v100, v101, vcc
	v_rsq_f32_e32 v102, v100
	v_lshl_add_u64 v[100:101], v[96:97], 2, s[14:15]
	v_mul_f32_e32 v103, 0x45800000, v102
	v_cndmask_b32_e32 v102, v102, v103, vcc
	v_mul_f32_e32 v88, v88, v102
	v_mul_f32_e32 v93, v93, v102
	v_mul_f32_e32 v89, v89, v102
	v_mul_f32_e32 v94, v94, v102
	v_mul_f32_e32 v90, v90, v102
	v_mul_f32_e32 v95, v95, v102
	v_mul_f32_e32 v92, v92, v102
	v_mul_f32_e32 v91, v91, v102
	v_mul_f32_e32 v103, v84, v102
	v_mul_f32_e32 v104, v80, v102
	v_mul_f32_e32 v105, v85, v102
	v_mul_f32_e32 v106, v81, v102
	v_mul_f32_e32 v86, v86, v102
	v_mul_f32_e32 v107, v82, v102
	v_mul_f32_e32 v108, v87, v102
	v_mul_f32_e32 v102, v83, v102
	v_max_f32_e32 v81, 0, v88
	v_max_f32_e32 v82, 0, v93
	v_max_f32_e32 v84, 0, v89
	v_max_f32_e32 v83, 0, v94
	v_max_f32_e32 v85, 0, v90
	v_max_f32_e32 v80, 0, v95
	v_max_f32_e32 v92, 0, v92
	v_max_f32_e32 v93, 0, v91
	v_max_f32_e32 v87, 0, v104
	v_max_f32_e32 v88, 0, v105
	v_max_f32_e32 v90, 0, v106
	v_max_f32_e32 v89, 0, v86
	v_max_f32_e32 v91, 0, v107
	v_max_f32_e32 v86, 0, v108
	v_pk_mul_f32 v[82:83], v[82:83], v[82:83]
	v_pk_mul_f32 v[80:81], v[80:81], v[80:81]
	v_pk_mul_f32 v[84:85], v[84:85], v[84:85]
	v_max_f32_e32 v94, 0, v103
	v_fma_mixlo_f16 v92, v92, v92, 0
	v_pk_mul_f32 v[88:89], v[88:89], v[88:89]
	v_pk_mul_f32 v[86:87], v[86:87], v[86:87]
	v_pk_mul_f32 v[90:91], v[90:91], v[90:91]
	v_cvt_pk_f16_f32 v82, v82, v83
	v_cvt_pk_f16_f32 v83, v80, v81
	v_cvt_pk_f16_f32 v84, v84, v85
	v_fma_mixlo_f16 v94, v94, v94, 0
	v_cvt_pk_f16_f32 v85, v88, v89
	v_cvt_pk_f16_f32 v86, v86, v87
	v_cvt_pk_f16_f32 v87, v90, v91
	v_pack_b32_f16 v80, v92, v82
	v_alignbit_b32 v81, v83, v82, 16
	v_alignbit_b32 v82, v84, v83, 16
	v_lshrrev_b32_e32 v83, 16, v84
	v_max_f32_e32 v95, 0, v102
	v_pack_b32_f16 v84, v94, v85
	v_alignbit_b32 v85, v86, v85, 16
	v_alignbit_b32 v86, v87, v86, 16
	v_lshrrev_b32_e32 v87, 16, v87
	v_fma_mixhi_f16 v83, v93, v93, 0
	v_fma_mixhi_f16 v87, v95, v95, 0
	global_store_dwordx4 v[98:99], v[80:83], off sc0 sc1
	global_store_dwordx4 v[98:99], v[84:87], off offset:256 sc0 sc1
	s_nop 1
	v_mov_b32_e32 v80, v184
	s_nop 0
	v_fmamk_f32 v80, v80, 0x3a800000, v171
	v_mul_f32_e32 v81, 0x4b800000, v80
;     __device__ __forceinline__ void operator()(const f32x4 (&acc)[2][2][4][2], const pg8::Unit& u, int wr, int wc, int fr, int fq) const {
;     ...
;                 const int row = row0 + ai * 128 + m * 16;
;                 float ss = 0.f, rstd = 1.f;
;                 if (MODE == 2) rstd = rsqrtf(rowss[row] * (1.f / 1024.f) + EPS);
; #pragma unroll
;                 for (int bj = 0; bj < 2; ++bj) {
;                     const int c = col0 + bj * 128;
;                     f32x4 v0 = acc[ai][bj][m][0], v1 = acc[ai][bj][m][1];
;                     if (MODE == 1) {
;                         const float* rp = res + (size_t)row * ldres + c;
;                         v0 += *(const f32x4*)rp; v1 += *(const f32x4*)(rp + 4);
;                     }
;                     if (MODE == 3) {
;                         const h16x8 r8 = *(const h16x8*)(res16 + (size_t)row * ldres + c);
; #pragma unroll
;                         for (int j = 0; j < 4; ++j) { v0[j] += (float)r8[j]; v1[j] += (float)r8[4 + j]; }
;                     }
;                     if (MODE == 1 || MODE == 3) {
;                         ss += v0[0] * v0[0] + v0[1] * v0[1] + v0[2] * v0[2] + v0[3] * v0[3] + v1[0] * v1[0] + v1[1] * v1[1] + v1[2] * v1[2] + v1[3] * v1[3];
;                     }
;                     if (MODE == 2) {
; #pragma unroll
;                         for (int j = 0; j < 4; ++j) { float a = fmaxf(v0[j] * rstd, 0.f), b = fmaxf(v1[j] * rstd, 0.f); v0[j] = a * a; v1[j] = b * b; }
;                     }
;                     *(h16x8*)(o16 + (size_t)row * ld16 + c) = pack8(v0, v1);
	v_cmp_gt_f32_e32 vcc, s53, v80
	s_nop 1
	v_cndmask_b32_e32 v80, v80, v81, vcc
	v_rsq_f32_e32 v82, v80
	v_lshlrev_b64 v[80:81], 13, v[96:97]
	v_lshl_add_u64 v[80:81], s[12:13], 0, v[80:81]
	v_lshl_add_u64 v[80:81], v[80:81], 0, v[164:165]
	v_mul_f32_e32 v83, 0x45800000, v82
	v_cndmask_b32_e32 v82, v82, v83, vcc
	v_mul_f32_e32 v72, v72, v82
	v_mul_f32_e32 v77, v77, v82
	v_mul_f32_e32 v73, v73, v82
	v_mul_f32_e32 v78, v78, v82
	v_mul_f32_e32 v74, v74, v82
	v_mul_f32_e32 v79, v79, v82
	v_mul_f32_e32 v76, v76, v82
	v_mul_f32_e32 v75, v75, v82
	v_mul_f32_e32 v83, v68, v82
	v_mul_f32_e32 v84, v64, v82
	v_mul_f32_e32 v85, v69, v82
	v_mul_f32_e32 v86, v65, v82
	v_mul_f32_e32 v70, v70, v82
	v_mul_f32_e32 v87, v66, v82
	v_mul_f32_e32 v88, v71, v82
	v_mul_f32_e32 v82, v67, v82
	v_max_f32_e32 v65, 0, v72
	v_max_f32_e32 v66, 0, v77
	v_max_f32_e32 v68, 0, v73
	v_max_f32_e32 v67, 0, v78
	v_max_f32_e32 v69, 0, v74
	v_max_f32_e32 v64, 0, v79
	v_max_f32_e32 v76, 0, v76
	v_max_f32_e32 v77, 0, v75
	v_max_f32_e32 v71, 0, v84
	v_max_f32_e32 v72, 0, v85
	v_max_f32_e32 v74, 0, v86
	v_max_f32_e32 v73, 0, v70
	v_max_f32_e32 v75, 0, v87
	v_max_f32_e32 v70, 0, v88
	v_pk_mul_f32 v[66:67], v[66:67], v[66:67]
	v_pk_mul_f32 v[64:65], v[64:65], v[64:65]
	v_pk_mul_f32 v[68:69], v[68:69], v[68:69]
	v_max_f32_e32 v78, 0, v83
	v_fma_mixlo_f16 v76, v76, v76, 0
	v_pk_mul_f32 v[72:73], v[72:73], v[72:73]
	v_pk_mul_f32 v[70:71], v[70:71], v[70:71]
	v_pk_mul_f32 v[74:75], v[74:75], v[74:75]
	v_cvt_pk_f16_f32 v66, v66, v67
	v_cvt_pk_f16_f32 v67, v64, v65
	v_cvt_pk_f16_f32 v68, v68, v69
	v_fma_mixlo_f16 v78, v78, v78, 0
	v_cvt_pk_f16_f32 v69, v72, v73
	v_cvt_pk_f16_f32 v70, v70, v71
	v_cvt_pk_f16_f32 v71, v74, v75
	v_pack_b32_f16 v64, v76, v66
	v_alignbit_b32 v65, v67, v66, 16
	v_alignbit_b32 v66, v68, v67, 16
	v_lshrrev_b32_e32 v67, 16, v68
	v_max_f32_e32 v79, 0, v82
	v_pack_b32_f16 v68, v78, v69
	v_alignbit_b32 v69, v70, v69, 16
	v_alignbit_b32 v70, v71, v70, 16
	v_lshrrev_b32_e32 v71, 16, v71
	v_fma_mixhi_f16 v67, v77, v77, 0
	v_fma_mixhi_f16 v71, v79, v79, 0
	global_store_dwordx4 v[80:81], v[64:67], off sc0 sc1
	global_store_dwordx4 v[80:81], v[68:71], off offset:256 sc0 sc1
	s_nop 1
	v_mov_b32_e32 v66, v185
	v_lshl_add_u64 v[64:65], v[162:163], 0, s[16:17]
	s_nop 0
	v_fmamk_f32 v66, v66, 0x3a800000, v171
	v_mul_f32_e32 v67, 0x4b800000, v66
	v_cmp_gt_f32_e32 vcc, s53, v66
	s_nop 1
	v_cndmask_b32_e32 v66, v66, v67, vcc
	v_rsq_f32_e32 v68, v66
	v_add_co_u32_e64 v66, s[0:1], s54, v162
	v_mul_f32_e32 v69, 0x45800000, v68
	v_cndmask_b32_e32 v68, v68, v69, vcc
	v_mul_f32_e32 v56, v56, v68
	v_mul_f32_e32 v61, v61, v68
	v_mul_f32_e32 v57, v57, v68
	v_mul_f32_e32 v62, v62, v68
	v_mul_f32_e32 v58, v58, v68
	v_mul_f32_e32 v63, v63, v68
	v_mul_f32_e32 v60, v60, v68
	v_mul_f32_e32 v59, v59, v68
	v_mul_f32_e32 v69, v52, v68
	v_mul_f32_e32 v70, v48, v68
	v_mul_f32_e32 v71, v53, v68
	v_mul_f32_e32 v72, v49, v68
	v_mul_f32_e32 v54, v54, v68
	v_mul_f32_e32 v73, v50, v68
	v_mul_f32_e32 v74, v55, v68
	v_mul_f32_e32 v68, v51, v68
	v_max_f32_e32 v49, 0, v56
	v_max_f32_e32 v50, 0, v61
	v_max_f32_e32 v52, 0, v57
	v_max_f32_e32 v51, 0, v62
	v_max_f32_e32 v53, 0, v58
	v_max_f32_e32 v48, 0, v63
	v_max_f32_e32 v60, 0, v60
	v_max_f32_e32 v61, 0, v59
	v_max_f32_e32 v55, 0, v70
	v_max_f32_e32 v56, 0, v71
	v_max_f32_e32 v58, 0, v72
	v_max_f32_e32 v57, 0, v54
	v_max_f32_e32 v59, 0, v73
	v_max_f32_e32 v54, 0, v74
	v_pk_mul_f32 v[50:51], v[50:51], v[50:51]
	v_pk_mul_f32 v[48:49], v[48:49], v[48:49]
	v_pk_mul_f32 v[52:53], v[52:53], v[52:53]
	v_max_f32_e32 v62, 0, v69
	v_fma_mixlo_f16 v60, v60, v60, 0
	v_pk_mul_f32 v[56:57], v[56:57], v[56:57]
	v_pk_mul_f32 v[54:55], v[54:55], v[54:55]
	v_pk_mul_f32 v[58:59], v[58:59], v[58:59]
	v_cvt_pk_f16_f32 v50, v50, v51
	v_cvt_pk_f16_f32 v51, v48, v49
	v_cvt_pk_f16_f32 v52, v52, v53
	v_fma_mixlo_f16 v62, v62, v62, 0
	v_cvt_pk_f16_f32 v53, v56, v57
	v_cvt_pk_f16_f32 v54, v54, v55
	v_cvt_pk_f16_f32 v55, v58, v59
	v_pack_b32_f16 v48, v60, v50
	v_alignbit_b32 v49, v51, v50, 16
	v_alignbit_b32 v50, v52, v51, 16
	v_lshrrev_b32_e32 v51, 16, v52
	v_addc_co_u32_e64 v67, s[0:1], 0, v163, s[0:1]
	v_max_f32_e32 v63, 0, v68
	v_pack_b32_f16 v52, v62, v53
	v_alignbit_b32 v53, v54, v53, 16
	v_alignbit_b32 v54, v55, v54, 16
	v_lshrrev_b32_e32 v55, 16, v55
	v_fma_mixhi_f16 v51, v61, v61, 0
	v_fma_mixhi_f16 v55, v63, v63, 0
	global_store_dwordx4 v[66:67], v[48:51], off sc0 sc1
	global_store_dwordx4 v[64:65], v[52:55], off offset:256 sc0 sc1
	s_nop 1
	v_mov_b32_e32 v50, v186
	v_lshl_add_u64 v[48:49], v[162:163], 0, s[18:19]
	s_nop 0
	v_fmamk_f32 v50, v50, 0x3a800000, v171
	v_mul_f32_e32 v51, 0x4b800000, v50
	v_cmp_gt_f32_e32 vcc, s53, v50
	s_nop 1
	v_cndmask_b32_e32 v50, v50, v51, vcc
	v_rsq_f32_e32 v52, v50
	v_add_co_u32_e64 v50, s[0:1], s55, v162
	v_mul_f32_e32 v53, 0x45800000, v52
	v_cndmask_b32_e32 v52, v52, v53, vcc
	v_mul_f32_e32 v40, v40, v52
	v_mul_f32_e32 v45, v45, v52
	v_mul_f32_e32 v41, v41, v52
	v_mul_f32_e32 v46, v46, v52
	v_mul_f32_e32 v42, v42, v52
	v_mul_f32_e32 v47, v47, v52
	v_mul_f32_e32 v44, v44, v52
	v_mul_f32_e32 v43, v43, v52
	v_mul_f32_e32 v53, v36, v52
	v_mul_f32_e32 v54, v32, v52
	v_mul_f32_e32 v55, v37, v52
	v_mul_f32_e32 v56, v33, v52
	v_mul_f32_e32 v38, v38, v52
	v_mul_f32_e32 v57, v34, v52
	v_mul_f32_e32 v58, v39, v52
	v_mul_f32_e32 v52, v35, v52
	v_max_f32_e32 v33, 0, v40
	v_max_f32_e32 v34, 0, v45
	v_max_f32_e32 v36, 0, v41
	v_max_f32_e32 v35, 0, v46
	v_max_f32_e32 v37, 0, v42
	v_max_f32_e32 v32, 0, v47
	v_max_f32_e32 v44, 0, v44
	v_max_f32_e32 v45, 0, v43
	v_max_f32_e32 v39, 0, v54
	v_max_f32_e32 v40, 0, v55
	v_max_f32_e32 v42, 0, v56
	v_max_f32_e32 v41, 0, v38
; template <class Epi>
; __device__ __forceinline__ void gemm_phase(LAS unsigned char* lds, const Gemm g, const StaticOrder& S, const Epi& E) {
;     ...
;         if constexpr (!Epi::AFTER_DRAIN) E(acc, cur, wr, wc, fr, fq);
;         if (!has_next) break;
;     __device__ __forceinline__ void operator()(const f32x4 (&acc)[2][2][4][2], const pg8::Unit& u, int wr, int wc, int fr, int fq) const {
;     ...
;                 const int row = row0 + ai * 128 + m * 16;
;                 float ss = 0.f, rstd = 1.f;
;                 if (MODE == 2) rstd = rsqrtf(rowss[row] * (1.f / 1024.f) + EPS);
; #pragma unroll
;                 for (int bj = 0; bj < 2; ++bj) {
;                     const int c = col0 + bj * 128;
;                     f32x4 v0 = acc[ai][bj][m][0], v1 = acc[ai][bj][m][1];
;                     if (MODE == 1) {
;                         const float* rp = res + (size_t)row * ldres + c;
;                         v0 += *(const f32x4*)rp; v1 += *(const f32x4*)(rp + 4);
;                     }
;                     if (MODE == 3) {
;                         const h16x8 r8 = *(const h16x8*)(res16 + (size_t)row * ldres + c);
; #pragma unroll
;                         for (int j = 0; j < 4; ++j) { v0[j] += (float)r8[j]; v1[j] += (float)r8[4 + j]; }
;                     }
;                     if (MODE == 1 || MODE == 3) {
;                         ss += v0[0] * v0[0] + v0[1] * v0[1] + v0[2] * v0[2] + v0[3] * v0[3] + v1[0] * v1[0] + v1[1] * v1[1] + v1[2] * v1[2] + v1[3] * v1[3];
;                     }
;                     if (MODE == 2) {
; #pragma unroll
;                         for (int j = 0; j < 4; ++j) { float a = fmaxf(v0[j] * rstd, 0.f), b = fmaxf(v1[j] * rstd, 0.f); v0[j] = a * a; v1[j] = b * b; }
;                     }
;                     *(h16x8*)(o16 + (size_t)row * ld16 + c) = pack8(v0, v1);
	v_max_f32_e32 v43, 0, v57
	v_max_f32_e32 v38, 0, v58
	v_pk_mul_f32 v[34:35], v[34:35], v[34:35]
	v_pk_mul_f32 v[32:33], v[32:33], v[32:33]
	v_pk_mul_f32 v[36:37], v[36:37], v[36:37]
	v_max_f32_e32 v46, 0, v53
	v_fma_mixlo_f16 v44, v44, v44, 0
	v_pk_mul_f32 v[40:41], v[40:41], v[40:41]
	v_pk_mul_f32 v[38:39], v[38:39], v[38:39]
	v_pk_mul_f32 v[42:43], v[42:43], v[42:43]
	v_cvt_pk_f16_f32 v34, v34, v35
	v_cvt_pk_f16_f32 v35, v32, v33
	v_cvt_pk_f16_f32 v36, v36, v37
	v_fma_mixlo_f16 v46, v46, v46, 0
	v_cvt_pk_f16_f32 v37, v40, v41
	v_cvt_pk_f16_f32 v38, v38, v39
	v_cvt_pk_f16_f32 v39, v42, v43
	v_pack_b32_f16 v32, v44, v34
	v_alignbit_b32 v33, v35, v34, 16
	v_alignbit_b32 v34, v36, v35, 16
	v_lshrrev_b32_e32 v35, 16, v36
	v_addc_co_u32_e64 v51, s[0:1], 0, v163, s[0:1]
	v_max_f32_e32 v47, 0, v52
	v_pack_b32_f16 v36, v46, v37
	v_alignbit_b32 v37, v38, v37, 16
	v_alignbit_b32 v38, v39, v38, 16
	v_lshrrev_b32_e32 v39, 16, v39
	v_fma_mixhi_f16 v35, v45, v45, 0
	v_fma_mixhi_f16 v39, v47, v47, 0
	global_store_dwordx4 v[50:51], v[32:35], off sc0 sc1
	global_store_dwordx4 v[48:49], v[36:39], off offset:256 sc0 sc1
	s_nop 1
	v_mov_b32_e32 v34, v187
	v_lshl_add_u64 v[32:33], v[162:163], 0, s[20:21]
	s_nop 0
	v_fmamk_f32 v34, v34, 0x3a800000, v171
	v_mul_f32_e32 v35, 0x4b800000, v34
	v_cmp_gt_f32_e32 vcc, s53, v34
	s_nop 1
	v_cndmask_b32_e32 v34, v34, v35, vcc
	v_rsq_f32_e32 v36, v34
	v_add_co_u32_e64 v34, s[0:1], s56, v162
	v_mul_f32_e32 v37, 0x45800000, v36
	v_cndmask_b32_e32 v36, v36, v37, vcc
	v_mul_f32_e32 v24, v24, v36
	v_mul_f32_e32 v29, v29, v36
	v_mul_f32_e32 v25, v25, v36
	v_mul_f32_e32 v30, v30, v36
	v_mul_f32_e32 v26, v26, v36
	v_mul_f32_e32 v31, v31, v36
	v_mul_f32_e32 v28, v28, v36
	v_mul_f32_e32 v27, v27, v36
	v_mul_f32_e32 v37, v20, v36
	v_mul_f32_e32 v38, v16, v36
	v_mul_f32_e32 v39, v21, v36
	v_mul_f32_e32 v40, v17, v36
	v_mul_f32_e32 v22, v22, v36
	v_mul_f32_e32 v41, v18, v36
	v_mul_f32_e32 v42, v23, v36
	v_mul_f32_e32 v36, v19, v36
	v_max_f32_e32 v17, 0, v24
	v_max_f32_e32 v18, 0, v29
	v_max_f32_e32 v20, 0, v25
	v_max_f32_e32 v19, 0, v30
	v_max_f32_e32 v21, 0, v26
	v_max_f32_e32 v16, 0, v31
	v_max_f32_e32 v28, 0, v28
	v_max_f32_e32 v29, 0, v27
	v_max_f32_e32 v23, 0, v38
	v_max_f32_e32 v24, 0, v39
	v_max_f32_e32 v26, 0, v40
	v_max_f32_e32 v25, 0, v22
	v_max_f32_e32 v27, 0, v41
	v_max_f32_e32 v22, 0, v42
	v_pk_mul_f32 v[18:19], v[18:19], v[18:19]
	v_pk_mul_f32 v[16:17], v[16:17], v[16:17]
	v_pk_mul_f32 v[20:21], v[20:21], v[20:21]
	v_max_f32_e32 v30, 0, v37
	v_fma_mixlo_f16 v28, v28, v28, 0
	v_pk_mul_f32 v[24:25], v[24:25], v[24:25]
	v_pk_mul_f32 v[22:23], v[22:23], v[22:23]
	v_pk_mul_f32 v[26:27], v[26:27], v[26:27]
	v_cvt_pk_f16_f32 v18, v18, v19
	v_cvt_pk_f16_f32 v19, v16, v17
	v_cvt_pk_f16_f32 v20, v20, v21
	v_fma_mixlo_f16 v30, v30, v30, 0
	v_cvt_pk_f16_f32 v21, v24, v25
	v_cvt_pk_f16_f32 v22, v22, v23
	v_cvt_pk_f16_f32 v23, v26, v27
	v_pack_b32_f16 v16, v28, v18
	v_alignbit_b32 v17, v19, v18, 16
	v_alignbit_b32 v18, v20, v19, 16
	v_lshrrev_b32_e32 v19, 16, v20
	v_addc_co_u32_e64 v35, s[0:1], 0, v163, s[0:1]
	v_max_f32_e32 v31, 0, v36
	v_pack_b32_f16 v20, v30, v21
	v_alignbit_b32 v21, v22, v21, 16
	v_alignbit_b32 v22, v23, v22, 16
	v_lshrrev_b32_e32 v23, 16, v23
	v_fma_mixhi_f16 v19, v29, v29, 0
	v_fma_mixhi_f16 v23, v31, v31, 0
	global_store_dwordx4 v[34:35], v[16:19], off sc0 sc1
	global_store_dwordx4 v[32:33], v[20:23], off offset:256 sc0 sc1
	s_nop 1
	v_mov_b32_e32 v18, v188
	s_and_b64 vcc, exec, s[6:7]
	v_lshl_add_u64 v[16:17], v[162:163], 0, s[22:23]
	s_nop 0
	v_fmamk_f32 v18, v18, 0x3a800000, v171
	v_mul_f32_e32 v19, 0x4b800000, v18
	v_cmp_gt_f32_e64 s[0:1], s53, v18
	s_nop 1
	v_cndmask_b32_e64 v18, v18, v19, s[0:1]
	v_rsq_f32_e32 v20, v18
	v_add_co_u32_e64 v18, s[6:7], s57, v162
	v_mul_f32_e32 v21, 0x45800000, v20
	v_cndmask_b32_e64 v20, v20, v21, s[0:1]
	v_mul_f32_e32 v8, v8, v20
	v_mul_f32_e32 v13, v13, v20
	v_mul_f32_e32 v9, v9, v20
	v_mul_f32_e32 v14, v14, v20
	v_mul_f32_e32 v10, v10, v20
	v_mul_f32_e32 v15, v15, v20
	v_mul_f32_e32 v12, v12, v20
	v_mul_f32_e32 v11, v11, v20
	v_mul_f32_e32 v21, v4, v20
	v_mul_f32_e32 v22, v0, v20
	v_mul_f32_e32 v23, v5, v20
	v_mul_f32_e32 v24, v1, v20
	v_mul_f32_e32 v6, v6, v20
	v_mul_f32_e32 v25, v2, v20
	v_mul_f32_e32 v26, v7, v20
	v_mul_f32_e32 v20, v3, v20
	v_max_f32_e32 v1, 0, v8
	v_max_f32_e32 v2, 0, v13
	v_max_f32_e32 v4, 0, v9
	v_max_f32_e32 v3, 0, v14
	v_max_f32_e32 v5, 0, v10
	v_max_f32_e32 v0, 0, v15
	v_max_f32_e32 v12, 0, v12
	v_max_f32_e32 v13, 0, v11
	v_max_f32_e32 v7, 0, v22
	v_max_f32_e32 v8, 0, v23
	v_max_f32_e32 v10, 0, v24
	v_max_f32_e32 v9, 0, v6
	v_max_f32_e32 v11, 0, v25
	v_max_f32_e32 v6, 0, v26
	v_pk_mul_f32 v[2:3], v[2:3], v[2:3]
	v_pk_mul_f32 v[0:1], v[0:1], v[0:1]
	v_pk_mul_f32 v[4:5], v[4:5], v[4:5]
	v_max_f32_e32 v14, 0, v21
	v_fma_mixlo_f16 v12, v12, v12, 0
	v_pk_mul_f32 v[8:9], v[8:9], v[8:9]
	v_pk_mul_f32 v[6:7], v[6:7], v[6:7]
	v_pk_mul_f32 v[10:11], v[10:11], v[10:11]
	v_cvt_pk_f16_f32 v2, v2, v3
	v_cvt_pk_f16_f32 v3, v0, v1
	v_cvt_pk_f16_f32 v4, v4, v5
	v_fma_mixlo_f16 v14, v14, v14, 0
	v_cvt_pk_f16_f32 v5, v8, v9
	v_cvt_pk_f16_f32 v6, v6, v7
	v_cvt_pk_f16_f32 v7, v10, v11
	v_pack_b32_f16 v0, v12, v2
	v_alignbit_b32 v1, v3, v2, 16
	v_alignbit_b32 v2, v4, v3, 16
	v_lshrrev_b32_e32 v3, 16, v4
	v_addc_co_u32_e64 v19, s[6:7], 0, v163, s[6:7]
	v_max_f32_e32 v15, 0, v20
	v_pack_b32_f16 v4, v14, v5
	v_alignbit_b32 v5, v6, v5, 16
	v_alignbit_b32 v6, v7, v6, 16
	v_lshrrev_b32_e32 v7, 16, v7
	v_fma_mixhi_f16 v3, v13, v13, 0
	v_fma_mixhi_f16 v7, v15, v15, 0
	global_store_dwordx4 v[18:19], v[0:3], off sc0 sc1
	global_store_dwordx4 v[16:17], v[4:7], off offset:256 sc0 sc1
	s_cbranch_vccz .LBB0_476
	s_waitcnt vmcnt(0)
	s_cmpk_gt_u32 s41, 0xff
	s_cbranch_scc1 .LBB0_487
	s_barrier
